# P6 chained epilogues: 8-bit gate loads batched 16 per half (was 48 serial load->wait round trips), same arithmetic
# speedup vs baseline: 1.0240x; 1.0129x over previous
;     __device__ __forceinline__ void operator()(f32x4 (&acc)[2][2][4][2], const Unit& u, int wr, int wc, int fr, int fq) const {
;         const bool second = u.pm >= 64; const int pm = second ? u.pm - 64 : u.pm, pn = second ? u.pn - 4 : u.pn;
;         const int row0 = pm * BM + wr * 64 + fr, col0 = pn * BM + wc * 32 + 8 * fq;
; #pragma unroll
;         for (int ai = 0; ai < 2; ++ai)
; #pragma unroll
;             for (int m = 0; m < 4; ++m) { const size_t row = (size_t)(row0 + ai * HALF + m * 16);
; #pragma unroll
;                 for (int bj = 0; bj < 2; ++bj) {
;                     const u32x2 gb = *(const u32x2*)(SG + row * SG_PITCH + 1024 + col0 + bj * HALF);
;                     float fb[8] = { (float)(gb.x & 255u), (float)((gb.x >> 8) & 255u), (float)((gb.x >> 16) & 255u), (float)(gb.x >> 24), (float)(gb.y & 255u), (float)((gb.y >> 8) & 255u), (float)((gb.y >> 16) & 255u), (float)(gb.y >> 24) };
; #pragma unroll
;                     for (int j = 0; j < 8; ++j) fb[j] = fmaxf(fb[j], 1.0f);
;                     if (!second) {
;                         const u32x2 ga = *(const u32x2*)(SG + row * SG_PITCH + col0 + bj * HALF);
;                         const float fa[8] = { (float)(ga.x & 255u), (float)((ga.x >> 8) & 255u), (float)((ga.x >> 16) & 255u), (float)(ga.x >> 24), (float)(ga.y & 255u), (float)((ga.y >> 8) & 255u), (float)((ga.y >> 16) & 255u), (float)(ga.y >> 24) };
; #pragma unroll
;                         for (int j = 0; j < 4; ++j) { acc[ai][bj][m][0][j] *= fa[j] * __builtin_amdgcn_rcpf(fb[j]); acc[ai][bj][m][1][j] *= fa[4 + j] * __builtin_amdgcn_rcpf(fb[4 + j]); }
.LBB0_650:
	s_lshl_b32 s15, s6, 8
	s_lshl_b32 s38, s38, 8
	s_add_i32 s17, s15, 0xffffc000
	s_add_i32 s39, s38, 0xfffffc00
	s_cmp_gt_i32 s6, 63
	s_cselect_b32 s15, s17, s15
	s_cselect_b32 s38, s39, s38
	v_add_u32_e32 v176, s15, v163
	v_or_b32_e32 v174, s38, v179
	v_mov_b32_e32 v175, 0
	s_cbranch_scc1 .Lp6_second
	v_mov_b32_e32 v216, v176
	v_mov_b64_e32 v[214:215], s[36:37]
	v_mad_i64_i32 v[214:215], s[98:99], v216, s56, v[214:215]
	v_lshl_add_u64 v[214:215], v[214:215], 0, v[174:175]
	global_load_dwordx2 v[182:183], v[214:215], off offset:1024
	global_load_dwordx2 v[184:185], v[214:215], off offset:1152
	global_load_dwordx2 v[198:199], v[214:215], off
	global_load_dwordx2 v[200:201], v[214:215], off offset:128
	v_add_u32_e32 v216, 16, v176
	v_mov_b64_e32 v[214:215], s[36:37]
	v_mad_i64_i32 v[214:215], s[98:99], v216, s56, v[214:215]
	v_lshl_add_u64 v[214:215], v[214:215], 0, v[174:175]
	global_load_dwordx2 v[186:187], v[214:215], off offset:1024
	global_load_dwordx2 v[188:189], v[214:215], off offset:1152
	global_load_dwordx2 v[202:203], v[214:215], off
	global_load_dwordx2 v[204:205], v[214:215], off offset:128
	v_add_u32_e32 v216, 32, v176
	v_mov_b64_e32 v[214:215], s[36:37]
	v_mad_i64_i32 v[214:215], s[98:99], v216, s56, v[214:215]
	v_lshl_add_u64 v[214:215], v[214:215], 0, v[174:175]
	global_load_dwordx2 v[190:191], v[214:215], off offset:1024
	global_load_dwordx2 v[192:193], v[214:215], off offset:1152
	global_load_dwordx2 v[206:207], v[214:215], off
	global_load_dwordx2 v[208:209], v[214:215], off offset:128
	v_add_u32_e32 v216, 48, v176
	v_mov_b64_e32 v[214:215], s[36:37]
	v_mad_i64_i32 v[214:215], s[98:99], v216, s56, v[214:215]
	v_lshl_add_u64 v[214:215], v[214:215], 0, v[174:175]
	global_load_dwordx2 v[194:195], v[214:215], off offset:1024
	global_load_dwordx2 v[196:197], v[214:215], off offset:1152
	global_load_dwordx2 v[210:211], v[214:215], off
	global_load_dwordx2 v[212:213], v[214:215], off offset:128
	s_waitcnt vmcnt(12)
	v_cvt_f32_ubyte0_e32 v218, v182
	v_cvt_f32_ubyte1_e32 v219, v182
	v_cvt_f32_ubyte2_e32 v220, v182
	v_cvt_f32_ubyte3_e32 v221, v182
	v_cvt_f32_ubyte0_e32 v222, v183
	v_cvt_f32_ubyte1_e32 v223, v183
	v_cvt_f32_ubyte2_e32 v224, v183
	v_cvt_f32_ubyte3_e32 v225, v183
	v_max_f32_e32 v218, 1.0, v218
	v_max_f32_e32 v219, 1.0, v219
	v_max_f32_e32 v220, 1.0, v220
	v_max_f32_e32 v221, 1.0, v221
	v_max_f32_e32 v222, 1.0, v222
	v_max_f32_e32 v223, 1.0, v223
	v_max_f32_e32 v224, 1.0, v224
	v_max_f32_e32 v225, 1.0, v225
	v_rcp_f32_e32 v218, v218
	v_rcp_f32_e32 v219, v219
	v_rcp_f32_e32 v220, v220
	v_rcp_f32_e32 v221, v221
	v_rcp_f32_e32 v222, v222
	v_rcp_f32_e32 v223, v223
	v_rcp_f32_e32 v224, v224
	v_rcp_f32_e32 v225, v225
	v_cvt_f32_ubyte0_e32 v228, v198
	v_cvt_f32_ubyte1_e32 v229, v198
	v_cvt_f32_ubyte2_e32 v230, v198
	v_cvt_f32_ubyte3_e32 v231, v198
	v_cvt_f32_ubyte0_e32 v232, v199
	v_cvt_f32_ubyte1_e32 v233, v199
	v_cvt_f32_ubyte2_e32 v234, v199
	v_cvt_f32_ubyte3_e32 v235, v199
	v_pk_mul_f32 v[218:219], v[218:219], v[228:229]
	v_pk_mul_f32 v[220:221], v[220:221], v[230:231]
	v_pk_mul_f32 v[222:223], v[222:223], v[232:233]
	v_pk_mul_f32 v[224:225], v[224:225], v[234:235]
	v_pk_mul_f32 v[16:17], v[36:37], v[218:219]
	v_pk_mul_f32 v[18:19], v[38:39], v[220:221]
	v_pk_mul_f32 v[20:21], v[32:33], v[222:223]
	v_pk_mul_f32 v[22:23], v[34:35], v[224:225]
	v_cvt_f32_ubyte0_e32 v218, v184
	v_cvt_f32_ubyte1_e32 v219, v184
	v_cvt_f32_ubyte2_e32 v220, v184
	v_cvt_f32_ubyte3_e32 v221, v184
	v_cvt_f32_ubyte0_e32 v222, v185
	v_cvt_f32_ubyte1_e32 v223, v185
	v_cvt_f32_ubyte2_e32 v224, v185
	v_cvt_f32_ubyte3_e32 v225, v185
	v_max_f32_e32 v218, 1.0, v218
	v_max_f32_e32 v219, 1.0, v219
	v_max_f32_e32 v220, 1.0, v220
	v_max_f32_e32 v221, 1.0, v221
	v_max_f32_e32 v222, 1.0, v222
	v_max_f32_e32 v223, 1.0, v223
	v_max_f32_e32 v224, 1.0, v224
	v_max_f32_e32 v225, 1.0, v225
	v_rcp_f32_e32 v218, v218
	v_rcp_f32_e32 v219, v219
	v_rcp_f32_e32 v220, v220
	v_rcp_f32_e32 v221, v221
	v_rcp_f32_e32 v222, v222
	v_rcp_f32_e32 v223, v223
	v_rcp_f32_e32 v224, v224
	v_rcp_f32_e32 v225, v225
	v_cvt_f32_ubyte0_e32 v228, v200
	v_cvt_f32_ubyte1_e32 v229, v200
	v_cvt_f32_ubyte2_e32 v230, v200
	v_cvt_f32_ubyte3_e32 v231, v200
	v_cvt_f32_ubyte0_e32 v232, v201
	v_cvt_f32_ubyte1_e32 v233, v201
	v_cvt_f32_ubyte2_e32 v234, v201
	v_cvt_f32_ubyte3_e32 v235, v201
	v_pk_mul_f32 v[218:219], v[218:219], v[228:229]
	v_pk_mul_f32 v[220:221], v[220:221], v[230:231]
	v_pk_mul_f32 v[222:223], v[222:223], v[232:233]
	v_pk_mul_f32 v[224:225], v[224:225], v[234:235]
	v_pk_mul_f32 v[32:33], v[156:157], v[218:219]
	v_pk_mul_f32 v[34:35], v[158:159], v[220:221]
	v_pk_mul_f32 v[36:37], v[152:153], v[222:223]
	v_pk_mul_f32 v[38:39], v[154:155], v[224:225]
	s_waitcnt vmcnt(8)
;     __device__ __forceinline__ void operator()(f32x4 (&acc)[2][2][4][2], const Unit& u, int wr, int wc, int fr, int fq) const {
;     ...
;                     const u32x2 gb = *(const u32x2*)(SG + row * SG_PITCH + 1024 + col0 + bj * HALF);
;                     float fb[8] = { (float)(gb.x & 255u), (float)((gb.x >> 8) & 255u), (float)((gb.x >> 16) & 255u), (float)(gb.x >> 24), (float)(gb.y & 255u), (float)((gb.y >> 8) & 255u), (float)((gb.y >> 16) & 255u), (float)(gb.y >> 24) };
; #pragma unroll
;                     for (int j = 0; j < 8; ++j) fb[j] = fmaxf(fb[j], 1.0f);
;                     if (!second) {
;                         const u32x2 ga = *(const u32x2*)(SG + row * SG_PITCH + col0 + bj * HALF);
;                         const float fa[8] = { (float)(ga.x & 255u), (float)((ga.x >> 8) & 255u), (float)((ga.x >> 16) & 255u), (float)(ga.x >> 24), (float)(ga.y & 255u), (float)((ga.y >> 8) & 255u), (float)((ga.y >> 16) & 255u), (float)(ga.y >> 24) };
; #pragma unroll
;                         for (int j = 0; j < 4; ++j) { acc[ai][bj][m][0][j] *= fa[j] * __builtin_amdgcn_rcpf(fb[j]); acc[ai][bj][m][1][j] *= fa[4 + j] * __builtin_amdgcn_rcpf(fb[4 + j]); }
	v_cvt_f32_ubyte0_e32 v218, v186
	v_cvt_f32_ubyte1_e32 v219, v186
	v_cvt_f32_ubyte2_e32 v220, v186
	v_cvt_f32_ubyte3_e32 v221, v186
	v_cvt_f32_ubyte0_e32 v222, v187
	v_cvt_f32_ubyte1_e32 v223, v187
	v_cvt_f32_ubyte2_e32 v224, v187
	v_cvt_f32_ubyte3_e32 v225, v187
	v_max_f32_e32 v218, 1.0, v218
	v_max_f32_e32 v219, 1.0, v219
	v_max_f32_e32 v220, 1.0, v220
	v_max_f32_e32 v221, 1.0, v221
	v_max_f32_e32 v222, 1.0, v222
	v_max_f32_e32 v223, 1.0, v223
	v_max_f32_e32 v224, 1.0, v224
	v_max_f32_e32 v225, 1.0, v225
	v_rcp_f32_e32 v218, v218
	v_rcp_f32_e32 v219, v219
	v_rcp_f32_e32 v220, v220
	v_rcp_f32_e32 v221, v221
	v_rcp_f32_e32 v222, v222
	v_rcp_f32_e32 v223, v223
	v_rcp_f32_e32 v224, v224
	v_rcp_f32_e32 v225, v225
	v_cvt_f32_ubyte0_e32 v228, v202
	v_cvt_f32_ubyte1_e32 v229, v202
	v_cvt_f32_ubyte2_e32 v230, v202
	v_cvt_f32_ubyte3_e32 v231, v202
	v_cvt_f32_ubyte0_e32 v232, v203
	v_cvt_f32_ubyte1_e32 v233, v203
	v_cvt_f32_ubyte2_e32 v234, v203
	v_cvt_f32_ubyte3_e32 v235, v203
	v_pk_mul_f32 v[218:219], v[218:219], v[228:229]
	v_pk_mul_f32 v[220:221], v[220:221], v[230:231]
	v_pk_mul_f32 v[222:223], v[222:223], v[232:233]
	v_pk_mul_f32 v[224:225], v[224:225], v[234:235]
	v_pk_mul_f32 v[48:49], v[68:69], v[218:219]
	v_pk_mul_f32 v[50:51], v[70:71], v[220:221]
	v_pk_mul_f32 v[52:53], v[64:65], v[222:223]
	v_pk_mul_f32 v[54:55], v[66:67], v[224:225]
	v_cvt_f32_ubyte0_e32 v218, v188
	v_cvt_f32_ubyte1_e32 v219, v188
	v_cvt_f32_ubyte2_e32 v220, v188
	v_cvt_f32_ubyte3_e32 v221, v188
	v_cvt_f32_ubyte0_e32 v222, v189
	v_cvt_f32_ubyte1_e32 v223, v189
	v_cvt_f32_ubyte2_e32 v224, v189
	v_cvt_f32_ubyte3_e32 v225, v189
	v_max_f32_e32 v218, 1.0, v218
	v_max_f32_e32 v219, 1.0, v219
	v_max_f32_e32 v220, 1.0, v220
	v_max_f32_e32 v221, 1.0, v221
	v_max_f32_e32 v222, 1.0, v222
	v_max_f32_e32 v223, 1.0, v223
	v_max_f32_e32 v224, 1.0, v224
	v_max_f32_e32 v225, 1.0, v225
	v_rcp_f32_e32 v218, v218
	v_rcp_f32_e32 v219, v219
	v_rcp_f32_e32 v220, v220
	v_rcp_f32_e32 v221, v221
	v_rcp_f32_e32 v222, v222
	v_rcp_f32_e32 v223, v223
	v_rcp_f32_e32 v224, v224
	v_rcp_f32_e32 v225, v225
	v_cvt_f32_ubyte0_e32 v228, v204
	v_cvt_f32_ubyte1_e32 v229, v204
	v_cvt_f32_ubyte2_e32 v230, v204
	v_cvt_f32_ubyte3_e32 v231, v204
	v_cvt_f32_ubyte0_e32 v232, v205
	v_cvt_f32_ubyte1_e32 v233, v205
	v_cvt_f32_ubyte2_e32 v234, v205
	v_cvt_f32_ubyte3_e32 v235, v205
	v_pk_mul_f32 v[218:219], v[218:219], v[228:229]
	v_pk_mul_f32 v[220:221], v[220:221], v[230:231]
	v_pk_mul_f32 v[222:223], v[222:223], v[232:233]
	v_pk_mul_f32 v[224:225], v[224:225], v[234:235]
	v_pk_mul_f32 v[64:65], v[148:149], v[218:219]
	v_pk_mul_f32 v[66:67], v[150:151], v[220:221]
	v_pk_mul_f32 v[68:69], v[144:145], v[222:223]
	v_pk_mul_f32 v[70:71], v[146:147], v[224:225]
	s_waitcnt vmcnt(4)
	v_cvt_f32_ubyte0_e32 v218, v190
	v_cvt_f32_ubyte1_e32 v219, v190
	v_cvt_f32_ubyte2_e32 v220, v190
	v_cvt_f32_ubyte3_e32 v221, v190
	v_cvt_f32_ubyte0_e32 v222, v191
	v_cvt_f32_ubyte1_e32 v223, v191
	v_cvt_f32_ubyte2_e32 v224, v191
	v_cvt_f32_ubyte3_e32 v225, v191
	v_max_f32_e32 v218, 1.0, v218
	v_max_f32_e32 v219, 1.0, v219
	v_max_f32_e32 v220, 1.0, v220
	v_max_f32_e32 v221, 1.0, v221
	v_max_f32_e32 v222, 1.0, v222
	v_max_f32_e32 v223, 1.0, v223
	v_max_f32_e32 v224, 1.0, v224
	v_max_f32_e32 v225, 1.0, v225
	v_rcp_f32_e32 v218, v218
	v_rcp_f32_e32 v219, v219
	v_rcp_f32_e32 v220, v220
	v_rcp_f32_e32 v221, v221
	v_rcp_f32_e32 v222, v222
	v_rcp_f32_e32 v223, v223
	v_rcp_f32_e32 v224, v224
	v_rcp_f32_e32 v225, v225
	v_cvt_f32_ubyte0_e32 v228, v206
	v_cvt_f32_ubyte1_e32 v229, v206
	v_cvt_f32_ubyte2_e32 v230, v206
	v_cvt_f32_ubyte3_e32 v231, v206
	v_cvt_f32_ubyte0_e32 v232, v207
	v_cvt_f32_ubyte1_e32 v233, v207
	v_cvt_f32_ubyte2_e32 v234, v207
	v_cvt_f32_ubyte3_e32 v235, v207
	v_pk_mul_f32 v[218:219], v[218:219], v[228:229]
	v_pk_mul_f32 v[220:221], v[220:221], v[230:231]
	v_pk_mul_f32 v[222:223], v[222:223], v[232:233]
	v_pk_mul_f32 v[224:225], v[224:225], v[234:235]
	v_pk_mul_f32 v[80:81], v[100:101], v[218:219]
	v_pk_mul_f32 v[82:83], v[102:103], v[220:221]
	v_pk_mul_f32 v[84:85], v[96:97], v[222:223]
	v_pk_mul_f32 v[86:87], v[98:99], v[224:225]
	v_cvt_f32_ubyte0_e32 v218, v192
	v_cvt_f32_ubyte1_e32 v219, v192
	v_cvt_f32_ubyte2_e32 v220, v192
	v_cvt_f32_ubyte3_e32 v221, v192
	v_cvt_f32_ubyte0_e32 v222, v193
	v_cvt_f32_ubyte1_e32 v223, v193
	v_cvt_f32_ubyte2_e32 v224, v193
	v_cvt_f32_ubyte3_e32 v225, v193
	v_max_f32_e32 v218, 1.0, v218
	v_max_f32_e32 v219, 1.0, v219
	v_max_f32_e32 v220, 1.0, v220
	v_max_f32_e32 v221, 1.0, v221
	v_max_f32_e32 v222, 1.0, v222
	v_max_f32_e32 v223, 1.0, v223
	v_max_f32_e32 v224, 1.0, v224
	v_max_f32_e32 v225, 1.0, v225
	v_rcp_f32_e32 v218, v218
	v_rcp_f32_e32 v219, v219
	v_rcp_f32_e32 v220, v220
	v_rcp_f32_e32 v221, v221
	v_rcp_f32_e32 v222, v222
	v_rcp_f32_e32 v223, v223
	v_rcp_f32_e32 v224, v224
	v_rcp_f32_e32 v225, v225
	v_cvt_f32_ubyte0_e32 v228, v208
	v_cvt_f32_ubyte1_e32 v229, v208
	v_cvt_f32_ubyte2_e32 v230, v208
	v_cvt_f32_ubyte3_e32 v231, v208
	v_cvt_f32_ubyte0_e32 v232, v209
	v_cvt_f32_ubyte1_e32 v233, v209
	v_cvt_f32_ubyte2_e32 v234, v209
	v_cvt_f32_ubyte3_e32 v235, v209
	v_pk_mul_f32 v[218:219], v[218:219], v[228:229]
	v_pk_mul_f32 v[220:221], v[220:221], v[230:231]
	v_pk_mul_f32 v[222:223], v[222:223], v[232:233]
	v_pk_mul_f32 v[224:225], v[224:225], v[234:235]
	v_pk_mul_f32 v[96:97], v[140:141], v[218:219]
	v_pk_mul_f32 v[98:99], v[142:143], v[220:221]
	v_pk_mul_f32 v[100:101], v[136:137], v[222:223]
	v_pk_mul_f32 v[102:103], v[138:139], v[224:225]
	s_waitcnt vmcnt(0)
;     __device__ __forceinline__ void operator()(f32x4 (&acc)[2][2][4][2], const Unit& u, int wr, int wc, int fr, int fq) const {
;     ...
;                     const u32x2 gb = *(const u32x2*)(SG + row * SG_PITCH + 1024 + col0 + bj * HALF);
;                     float fb[8] = { (float)(gb.x & 255u), (float)((gb.x >> 8) & 255u), (float)((gb.x >> 16) & 255u), (float)(gb.x >> 24), (float)(gb.y & 255u), (float)((gb.y >> 8) & 255u), (float)((gb.y >> 16) & 255u), (float)(gb.y >> 24) };
; #pragma unroll
;                     for (int j = 0; j < 8; ++j) fb[j] = fmaxf(fb[j], 1.0f);
;                     if (!second) {
;                         const u32x2 ga = *(const u32x2*)(SG + row * SG_PITCH + col0 + bj * HALF);
;                         const float fa[8] = { (float)(ga.x & 255u), (float)((ga.x >> 8) & 255u), (float)((ga.x >> 16) & 255u), (float)(ga.x >> 24), (float)(ga.y & 255u), (float)((ga.y >> 8) & 255u), (float)((ga.y >> 16) & 255u), (float)(ga.y >> 24) };
; #pragma unroll
;                         for (int j = 0; j < 4; ++j) { acc[ai][bj][m][0][j] *= fa[j] * __builtin_amdgcn_rcpf(fb[j]); acc[ai][bj][m][1][j] *= fa[4 + j] * __builtin_amdgcn_rcpf(fb[4 + j]); }
	v_cvt_f32_ubyte0_e32 v218, v194
	v_cvt_f32_ubyte1_e32 v219, v194
	v_cvt_f32_ubyte2_e32 v220, v194
	v_cvt_f32_ubyte3_e32 v221, v194
	v_cvt_f32_ubyte0_e32 v222, v195
	v_cvt_f32_ubyte1_e32 v223, v195
	v_cvt_f32_ubyte2_e32 v224, v195
	v_cvt_f32_ubyte3_e32 v225, v195
	v_max_f32_e32 v218, 1.0, v218
	v_max_f32_e32 v219, 1.0, v219
	v_max_f32_e32 v220, 1.0, v220
	v_max_f32_e32 v221, 1.0, v221
	v_max_f32_e32 v222, 1.0, v222
	v_max_f32_e32 v223, 1.0, v223
	v_max_f32_e32 v224, 1.0, v224
	v_max_f32_e32 v225, 1.0, v225
	v_rcp_f32_e32 v218, v218
	v_rcp_f32_e32 v219, v219
	v_rcp_f32_e32 v220, v220
	v_rcp_f32_e32 v221, v221
	v_rcp_f32_e32 v222, v222
	v_rcp_f32_e32 v223, v223
	v_rcp_f32_e32 v224, v224
	v_rcp_f32_e32 v225, v225
	v_cvt_f32_ubyte0_e32 v228, v210
	v_cvt_f32_ubyte1_e32 v229, v210
	v_cvt_f32_ubyte2_e32 v230, v210
	v_cvt_f32_ubyte3_e32 v231, v210
	v_cvt_f32_ubyte0_e32 v232, v211
	v_cvt_f32_ubyte1_e32 v233, v211
	v_cvt_f32_ubyte2_e32 v234, v211
	v_cvt_f32_ubyte3_e32 v235, v211
	v_pk_mul_f32 v[218:219], v[218:219], v[228:229]
	v_pk_mul_f32 v[220:221], v[220:221], v[230:231]
	v_pk_mul_f32 v[222:223], v[222:223], v[232:233]
	v_pk_mul_f32 v[224:225], v[224:225], v[234:235]
	v_pk_mul_f32 v[112:113], v[132:133], v[218:219]
	v_pk_mul_f32 v[114:115], v[134:135], v[220:221]
	v_pk_mul_f32 v[116:117], v[128:129], v[222:223]
	v_pk_mul_f32 v[118:119], v[130:131], v[224:225]
	v_cvt_f32_ubyte0_e32 v218, v196
	v_cvt_f32_ubyte1_e32 v219, v196
	v_cvt_f32_ubyte2_e32 v220, v196
	v_cvt_f32_ubyte3_e32 v221, v196
	v_cvt_f32_ubyte0_e32 v222, v197
	v_cvt_f32_ubyte1_e32 v223, v197
	v_cvt_f32_ubyte2_e32 v224, v197
	v_cvt_f32_ubyte3_e32 v225, v197
	v_max_f32_e32 v218, 1.0, v218
	v_max_f32_e32 v219, 1.0, v219
	v_max_f32_e32 v220, 1.0, v220
	v_max_f32_e32 v221, 1.0, v221
	v_max_f32_e32 v222, 1.0, v222
	v_max_f32_e32 v223, 1.0, v223
	v_max_f32_e32 v224, 1.0, v224
	v_max_f32_e32 v225, 1.0, v225
	v_rcp_f32_e32 v218, v218
	v_rcp_f32_e32 v219, v219
	v_rcp_f32_e32 v220, v220
	v_rcp_f32_e32 v221, v221
	v_rcp_f32_e32 v222, v222
	v_rcp_f32_e32 v223, v223
	v_rcp_f32_e32 v224, v224
	v_rcp_f32_e32 v225, v225
	v_cvt_f32_ubyte0_e32 v228, v212
	v_cvt_f32_ubyte1_e32 v229, v212
	v_cvt_f32_ubyte2_e32 v230, v212
	v_cvt_f32_ubyte3_e32 v231, v212
	v_cvt_f32_ubyte0_e32 v232, v213
	v_cvt_f32_ubyte1_e32 v233, v213
	v_cvt_f32_ubyte2_e32 v234, v213
	v_cvt_f32_ubyte3_e32 v235, v213
	v_pk_mul_f32 v[218:219], v[218:219], v[228:229]
	v_pk_mul_f32 v[220:221], v[220:221], v[230:231]
	v_pk_mul_f32 v[222:223], v[222:223], v[232:233]
	v_pk_mul_f32 v[224:225], v[224:225], v[234:235]
	v_pk_mul_f32 v[128:129], v[124:125], v[218:219]
	v_pk_mul_f32 v[130:131], v[126:127], v[220:221]
	v_pk_mul_f32 v[132:133], v[120:121], v[222:223]
	v_pk_mul_f32 v[134:135], v[122:123], v[224:225]
	v_add_u32_e32 v216, 128, v176
	v_mov_b64_e32 v[214:215], s[36:37]
	v_mad_i64_i32 v[214:215], s[98:99], v216, s56, v[214:215]
	v_lshl_add_u64 v[214:215], v[214:215], 0, v[174:175]
	global_load_dwordx2 v[182:183], v[214:215], off offset:1024
	global_load_dwordx2 v[184:185], v[214:215], off offset:1152
	global_load_dwordx2 v[198:199], v[214:215], off
	global_load_dwordx2 v[200:201], v[214:215], off offset:128
	v_add_u32_e32 v216, 144, v176
	v_mov_b64_e32 v[214:215], s[36:37]
	v_mad_i64_i32 v[214:215], s[98:99], v216, s56, v[214:215]
	v_lshl_add_u64 v[214:215], v[214:215], 0, v[174:175]
	global_load_dwordx2 v[186:187], v[214:215], off offset:1024
	global_load_dwordx2 v[188:189], v[214:215], off offset:1152
	global_load_dwordx2 v[202:203], v[214:215], off
	global_load_dwordx2 v[204:205], v[214:215], off offset:128
	v_add_u32_e32 v216, 160, v176
	v_mov_b64_e32 v[214:215], s[36:37]
	v_mad_i64_i32 v[214:215], s[98:99], v216, s56, v[214:215]
	v_lshl_add_u64 v[214:215], v[214:215], 0, v[174:175]
	global_load_dwordx2 v[190:191], v[214:215], off offset:1024
	global_load_dwordx2 v[192:193], v[214:215], off offset:1152
	global_load_dwordx2 v[206:207], v[214:215], off
	global_load_dwordx2 v[208:209], v[214:215], off offset:128
	v_add_u32_e32 v216, 176, v176
	v_mov_b64_e32 v[214:215], s[36:37]
	v_mad_i64_i32 v[214:215], s[98:99], v216, s56, v[214:215]
	v_lshl_add_u64 v[214:215], v[214:215], 0, v[174:175]
	global_load_dwordx2 v[194:195], v[214:215], off offset:1024
	global_load_dwordx2 v[196:197], v[214:215], off offset:1152
	global_load_dwordx2 v[210:211], v[214:215], off
	global_load_dwordx2 v[212:213], v[214:215], off offset:128
	s_waitcnt vmcnt(12)
;     __device__ __forceinline__ void operator()(f32x4 (&acc)[2][2][4][2], const Unit& u, int wr, int wc, int fr, int fq) const {
;     ...
;                     const u32x2 gb = *(const u32x2*)(SG + row * SG_PITCH + 1024 + col0 + bj * HALF);
;                     float fb[8] = { (float)(gb.x & 255u), (float)((gb.x >> 8) & 255u), (float)((gb.x >> 16) & 255u), (float)(gb.x >> 24), (float)(gb.y & 255u), (float)((gb.y >> 8) & 255u), (float)((gb.y >> 16) & 255u), (float)(gb.y >> 24) };
; #pragma unroll
;                     for (int j = 0; j < 8; ++j) fb[j] = fmaxf(fb[j], 1.0f);
;                     if (!second) {
;                         const u32x2 ga = *(const u32x2*)(SG + row * SG_PITCH + col0 + bj * HALF);
;                         const float fa[8] = { (float)(ga.x & 255u), (float)((ga.x >> 8) & 255u), (float)((ga.x >> 16) & 255u), (float)(ga.x >> 24), (float)(ga.y & 255u), (float)((ga.y >> 8) & 255u), (float)((ga.y >> 16) & 255u), (float)(ga.y >> 24) };
; #pragma unroll
;                         for (int j = 0; j < 4; ++j) { acc[ai][bj][m][0][j] *= fa[j] * __builtin_amdgcn_rcpf(fb[j]); acc[ai][bj][m][1][j] *= fa[4 + j] * __builtin_amdgcn_rcpf(fb[4 + j]); }
	v_cvt_f32_ubyte0_e32 v218, v182
	v_cvt_f32_ubyte1_e32 v219, v182
	v_cvt_f32_ubyte2_e32 v220, v182
	v_cvt_f32_ubyte3_e32 v221, v182
	v_cvt_f32_ubyte0_e32 v222, v183
	v_cvt_f32_ubyte1_e32 v223, v183
	v_cvt_f32_ubyte2_e32 v224, v183
	v_cvt_f32_ubyte3_e32 v225, v183
	v_max_f32_e32 v218, 1.0, v218
	v_max_f32_e32 v219, 1.0, v219
	v_max_f32_e32 v220, 1.0, v220
	v_max_f32_e32 v221, 1.0, v221
	v_max_f32_e32 v222, 1.0, v222
	v_max_f32_e32 v223, 1.0, v223
	v_max_f32_e32 v224, 1.0, v224
	v_max_f32_e32 v225, 1.0, v225
	v_rcp_f32_e32 v218, v218
	v_rcp_f32_e32 v219, v219
	v_rcp_f32_e32 v220, v220
	v_rcp_f32_e32 v221, v221
	v_rcp_f32_e32 v222, v222
	v_rcp_f32_e32 v223, v223
	v_rcp_f32_e32 v224, v224
	v_rcp_f32_e32 v225, v225
	v_cvt_f32_ubyte0_e32 v228, v198
	v_cvt_f32_ubyte1_e32 v229, v198
	v_cvt_f32_ubyte2_e32 v230, v198
	v_cvt_f32_ubyte3_e32 v231, v198
	v_cvt_f32_ubyte0_e32 v232, v199
	v_cvt_f32_ubyte1_e32 v233, v199
	v_cvt_f32_ubyte2_e32 v234, v199
	v_cvt_f32_ubyte3_e32 v235, v199
	v_pk_mul_f32 v[218:219], v[218:219], v[228:229]
	v_pk_mul_f32 v[220:221], v[220:221], v[230:231]
	v_pk_mul_f32 v[222:223], v[222:223], v[232:233]
	v_pk_mul_f32 v[224:225], v[224:225], v[234:235]
	v_pk_mul_f32 v[120:121], v[108:109], v[218:219]
	v_pk_mul_f32 v[122:123], v[110:111], v[220:221]
	v_pk_mul_f32 v[124:125], v[104:105], v[222:223]
	v_pk_mul_f32 v[126:127], v[106:107], v[224:225]
	v_cvt_f32_ubyte0_e32 v218, v184
	v_cvt_f32_ubyte1_e32 v219, v184
	v_cvt_f32_ubyte2_e32 v220, v184
	v_cvt_f32_ubyte3_e32 v221, v184
	v_cvt_f32_ubyte0_e32 v222, v185
	v_cvt_f32_ubyte1_e32 v223, v185
	v_cvt_f32_ubyte2_e32 v224, v185
	v_cvt_f32_ubyte3_e32 v225, v185
	v_max_f32_e32 v218, 1.0, v218
	v_max_f32_e32 v219, 1.0, v219
	v_max_f32_e32 v220, 1.0, v220
	v_max_f32_e32 v221, 1.0, v221
	v_max_f32_e32 v222, 1.0, v222
	v_max_f32_e32 v223, 1.0, v223
	v_max_f32_e32 v224, 1.0, v224
	v_max_f32_e32 v225, 1.0, v225
	v_rcp_f32_e32 v218, v218
	v_rcp_f32_e32 v219, v219
	v_rcp_f32_e32 v220, v220
	v_rcp_f32_e32 v221, v221
	v_rcp_f32_e32 v222, v222
	v_rcp_f32_e32 v223, v223
	v_rcp_f32_e32 v224, v224
	v_rcp_f32_e32 v225, v225
	v_cvt_f32_ubyte0_e32 v228, v200
	v_cvt_f32_ubyte1_e32 v229, v200
	v_cvt_f32_ubyte2_e32 v230, v200
	v_cvt_f32_ubyte3_e32 v231, v200
	v_cvt_f32_ubyte0_e32 v232, v201
	v_cvt_f32_ubyte1_e32 v233, v201
	v_cvt_f32_ubyte2_e32 v234, v201
	v_cvt_f32_ubyte3_e32 v235, v201
	v_pk_mul_f32 v[218:219], v[218:219], v[228:229]
	v_pk_mul_f32 v[220:221], v[220:221], v[230:231]
	v_pk_mul_f32 v[222:223], v[222:223], v[232:233]
	v_pk_mul_f32 v[224:225], v[224:225], v[234:235]
	v_pk_mul_f32 v[104:105], v[92:93], v[218:219]
	v_pk_mul_f32 v[106:107], v[94:95], v[220:221]
	v_pk_mul_f32 v[108:109], v[88:89], v[222:223]
	v_pk_mul_f32 v[110:111], v[90:91], v[224:225]
	s_waitcnt vmcnt(8)
	v_cvt_f32_ubyte0_e32 v218, v186
	v_cvt_f32_ubyte1_e32 v219, v186
	v_cvt_f32_ubyte2_e32 v220, v186
	v_cvt_f32_ubyte3_e32 v221, v186
	v_cvt_f32_ubyte0_e32 v222, v187
	v_cvt_f32_ubyte1_e32 v223, v187
	v_cvt_f32_ubyte2_e32 v224, v187
	v_cvt_f32_ubyte3_e32 v225, v187
	v_max_f32_e32 v218, 1.0, v218
	v_max_f32_e32 v219, 1.0, v219
	v_max_f32_e32 v220, 1.0, v220
	v_max_f32_e32 v221, 1.0, v221
	v_max_f32_e32 v222, 1.0, v222
	v_max_f32_e32 v223, 1.0, v223
	v_max_f32_e32 v224, 1.0, v224
	v_max_f32_e32 v225, 1.0, v225
	v_rcp_f32_e32 v218, v218
	v_rcp_f32_e32 v219, v219
	v_rcp_f32_e32 v220, v220
	v_rcp_f32_e32 v221, v221
	v_rcp_f32_e32 v222, v222
	v_rcp_f32_e32 v223, v223
	v_rcp_f32_e32 v224, v224
	v_rcp_f32_e32 v225, v225
	v_cvt_f32_ubyte0_e32 v228, v202
	v_cvt_f32_ubyte1_e32 v229, v202
	v_cvt_f32_ubyte2_e32 v230, v202
	v_cvt_f32_ubyte3_e32 v231, v202
	v_cvt_f32_ubyte0_e32 v232, v203
	v_cvt_f32_ubyte1_e32 v233, v203
	v_cvt_f32_ubyte2_e32 v234, v203
	v_cvt_f32_ubyte3_e32 v235, v203
	v_pk_mul_f32 v[218:219], v[218:219], v[228:229]
	v_pk_mul_f32 v[220:221], v[220:221], v[230:231]
	v_pk_mul_f32 v[222:223], v[222:223], v[232:233]
	v_pk_mul_f32 v[224:225], v[224:225], v[234:235]
	v_pk_mul_f32 v[136:137], v[76:77], v[218:219]
	v_pk_mul_f32 v[138:139], v[78:79], v[220:221]
	v_pk_mul_f32 v[140:141], v[72:73], v[222:223]
	v_pk_mul_f32 v[142:143], v[74:75], v[224:225]
	v_cvt_f32_ubyte0_e32 v218, v188
	v_cvt_f32_ubyte1_e32 v219, v188
	v_cvt_f32_ubyte2_e32 v220, v188
	v_cvt_f32_ubyte3_e32 v221, v188
	v_cvt_f32_ubyte0_e32 v222, v189
	v_cvt_f32_ubyte1_e32 v223, v189
	v_cvt_f32_ubyte2_e32 v224, v189
	v_cvt_f32_ubyte3_e32 v225, v189
	v_max_f32_e32 v218, 1.0, v218
	v_max_f32_e32 v219, 1.0, v219
	v_max_f32_e32 v220, 1.0, v220
	v_max_f32_e32 v221, 1.0, v221
	v_max_f32_e32 v222, 1.0, v222
	v_max_f32_e32 v223, 1.0, v223
	v_max_f32_e32 v224, 1.0, v224
	v_max_f32_e32 v225, 1.0, v225
	v_rcp_f32_e32 v218, v218
	v_rcp_f32_e32 v219, v219
	v_rcp_f32_e32 v220, v220
	v_rcp_f32_e32 v221, v221
	v_rcp_f32_e32 v222, v222
	v_rcp_f32_e32 v223, v223
	v_rcp_f32_e32 v224, v224
	v_rcp_f32_e32 v225, v225
	v_cvt_f32_ubyte0_e32 v228, v204
	v_cvt_f32_ubyte1_e32 v229, v204
	v_cvt_f32_ubyte2_e32 v230, v204
	v_cvt_f32_ubyte3_e32 v231, v204
	v_cvt_f32_ubyte0_e32 v232, v205
	v_cvt_f32_ubyte1_e32 v233, v205
	v_cvt_f32_ubyte2_e32 v234, v205
	v_cvt_f32_ubyte3_e32 v235, v205
	v_pk_mul_f32 v[218:219], v[218:219], v[228:229]
	v_pk_mul_f32 v[220:221], v[220:221], v[230:231]
	v_pk_mul_f32 v[222:223], v[222:223], v[232:233]
	v_pk_mul_f32 v[224:225], v[224:225], v[234:235]
	v_pk_mul_f32 v[72:73], v[60:61], v[218:219]
	v_pk_mul_f32 v[74:75], v[62:63], v[220:221]
	v_pk_mul_f32 v[76:77], v[56:57], v[222:223]
	v_pk_mul_f32 v[78:79], v[58:59], v[224:225]
	s_waitcnt vmcnt(4)
;     __device__ __forceinline__ void operator()(f32x4 (&acc)[2][2][4][2], const Unit& u, int wr, int wc, int fr, int fq) const {
;     ...
;                     const u32x2 gb = *(const u32x2*)(SG + row * SG_PITCH + 1024 + col0 + bj * HALF);
;                     float fb[8] = { (float)(gb.x & 255u), (float)((gb.x >> 8) & 255u), (float)((gb.x >> 16) & 255u), (float)(gb.x >> 24), (float)(gb.y & 255u), (float)((gb.y >> 8) & 255u), (float)((gb.y >> 16) & 255u), (float)(gb.y >> 24) };
; #pragma unroll
;                     for (int j = 0; j < 8; ++j) fb[j] = fmaxf(fb[j], 1.0f);
;                     if (!second) {
;                         const u32x2 ga = *(const u32x2*)(SG + row * SG_PITCH + col0 + bj * HALF);
;                         const float fa[8] = { (float)(ga.x & 255u), (float)((ga.x >> 8) & 255u), (float)((ga.x >> 16) & 255u), (float)(ga.x >> 24), (float)(ga.y & 255u), (float)((ga.y >> 8) & 255u), (float)((ga.y >> 16) & 255u), (float)(ga.y >> 24) };
; #pragma unroll
;                         for (int j = 0; j < 4; ++j) { acc[ai][bj][m][0][j] *= fa[j] * __builtin_amdgcn_rcpf(fb[j]); acc[ai][bj][m][1][j] *= fa[4 + j] * __builtin_amdgcn_rcpf(fb[4 + j]); }
	v_cvt_f32_ubyte0_e32 v218, v190
	v_cvt_f32_ubyte1_e32 v219, v190
	v_cvt_f32_ubyte2_e32 v220, v190
	v_cvt_f32_ubyte3_e32 v221, v190
	v_cvt_f32_ubyte0_e32 v222, v191
	v_cvt_f32_ubyte1_e32 v223, v191
	v_cvt_f32_ubyte2_e32 v224, v191
	v_cvt_f32_ubyte3_e32 v225, v191
	v_max_f32_e32 v218, 1.0, v218
	v_max_f32_e32 v219, 1.0, v219
	v_max_f32_e32 v220, 1.0, v220
	v_max_f32_e32 v221, 1.0, v221
	v_max_f32_e32 v222, 1.0, v222
	v_max_f32_e32 v223, 1.0, v223
	v_max_f32_e32 v224, 1.0, v224
	v_max_f32_e32 v225, 1.0, v225
	v_rcp_f32_e32 v218, v218
	v_rcp_f32_e32 v219, v219
	v_rcp_f32_e32 v220, v220
	v_rcp_f32_e32 v221, v221
	v_rcp_f32_e32 v222, v222
	v_rcp_f32_e32 v223, v223
	v_rcp_f32_e32 v224, v224
	v_rcp_f32_e32 v225, v225
	v_cvt_f32_ubyte0_e32 v228, v206
	v_cvt_f32_ubyte1_e32 v229, v206
	v_cvt_f32_ubyte2_e32 v230, v206
	v_cvt_f32_ubyte3_e32 v231, v206
	v_cvt_f32_ubyte0_e32 v232, v207
	v_cvt_f32_ubyte1_e32 v233, v207
	v_cvt_f32_ubyte2_e32 v234, v207
	v_cvt_f32_ubyte3_e32 v235, v207
	v_pk_mul_f32 v[218:219], v[218:219], v[228:229]
	v_pk_mul_f32 v[220:221], v[220:221], v[230:231]
	v_pk_mul_f32 v[222:223], v[222:223], v[232:233]
	v_pk_mul_f32 v[224:225], v[224:225], v[234:235]
	v_pk_mul_f32 v[144:145], v[44:45], v[218:219]
	v_pk_mul_f32 v[146:147], v[46:47], v[220:221]
	v_pk_mul_f32 v[148:149], v[40:41], v[222:223]
	v_pk_mul_f32 v[150:151], v[42:43], v[224:225]
	v_cvt_f32_ubyte0_e32 v218, v192
	v_cvt_f32_ubyte1_e32 v219, v192
	v_cvt_f32_ubyte2_e32 v220, v192
	v_cvt_f32_ubyte3_e32 v221, v192
	v_cvt_f32_ubyte0_e32 v222, v193
	v_cvt_f32_ubyte1_e32 v223, v193
	v_cvt_f32_ubyte2_e32 v224, v193
	v_cvt_f32_ubyte3_e32 v225, v193
	v_max_f32_e32 v218, 1.0, v218
	v_max_f32_e32 v219, 1.0, v219
	v_max_f32_e32 v220, 1.0, v220
	v_max_f32_e32 v221, 1.0, v221
	v_max_f32_e32 v222, 1.0, v222
	v_max_f32_e32 v223, 1.0, v223
	v_max_f32_e32 v224, 1.0, v224
	v_max_f32_e32 v225, 1.0, v225
	v_rcp_f32_e32 v218, v218
	v_rcp_f32_e32 v219, v219
	v_rcp_f32_e32 v220, v220
	v_rcp_f32_e32 v221, v221
	v_rcp_f32_e32 v222, v222
	v_rcp_f32_e32 v223, v223
	v_rcp_f32_e32 v224, v224
	v_rcp_f32_e32 v225, v225
	v_cvt_f32_ubyte0_e32 v228, v208
	v_cvt_f32_ubyte1_e32 v229, v208
	v_cvt_f32_ubyte2_e32 v230, v208
	v_cvt_f32_ubyte3_e32 v231, v208
	v_cvt_f32_ubyte0_e32 v232, v209
	v_cvt_f32_ubyte1_e32 v233, v209
	v_cvt_f32_ubyte2_e32 v234, v209
	v_cvt_f32_ubyte3_e32 v235, v209
	v_pk_mul_f32 v[218:219], v[218:219], v[228:229]
	v_pk_mul_f32 v[220:221], v[220:221], v[230:231]
	v_pk_mul_f32 v[222:223], v[222:223], v[232:233]
	v_pk_mul_f32 v[224:225], v[224:225], v[234:235]
	v_pk_mul_f32 v[40:41], v[28:29], v[218:219]
	v_pk_mul_f32 v[42:43], v[30:31], v[220:221]
	v_pk_mul_f32 v[44:45], v[24:25], v[222:223]
	v_pk_mul_f32 v[46:47], v[26:27], v[224:225]
	s_waitcnt vmcnt(0)
	v_cvt_f32_ubyte0_e32 v218, v194
	v_cvt_f32_ubyte1_e32 v219, v194
	v_cvt_f32_ubyte2_e32 v220, v194
	v_cvt_f32_ubyte3_e32 v221, v194
	v_cvt_f32_ubyte0_e32 v222, v195
	v_cvt_f32_ubyte1_e32 v223, v195
	v_cvt_f32_ubyte2_e32 v224, v195
	v_cvt_f32_ubyte3_e32 v225, v195
	v_max_f32_e32 v218, 1.0, v218
	v_max_f32_e32 v219, 1.0, v219
	v_max_f32_e32 v220, 1.0, v220
	v_max_f32_e32 v221, 1.0, v221
	v_max_f32_e32 v222, 1.0, v222
	v_max_f32_e32 v223, 1.0, v223
	v_max_f32_e32 v224, 1.0, v224
	v_max_f32_e32 v225, 1.0, v225
	v_rcp_f32_e32 v218, v218
	v_rcp_f32_e32 v219, v219
	v_rcp_f32_e32 v220, v220
	v_rcp_f32_e32 v221, v221
	v_rcp_f32_e32 v222, v222
	v_rcp_f32_e32 v223, v223
	v_rcp_f32_e32 v224, v224
	v_rcp_f32_e32 v225, v225
	v_cvt_f32_ubyte0_e32 v228, v210
	v_cvt_f32_ubyte1_e32 v229, v210
	v_cvt_f32_ubyte2_e32 v230, v210
	v_cvt_f32_ubyte3_e32 v231, v210
	v_cvt_f32_ubyte0_e32 v232, v211
	v_cvt_f32_ubyte1_e32 v233, v211
	v_cvt_f32_ubyte2_e32 v234, v211
	v_cvt_f32_ubyte3_e32 v235, v211
	v_pk_mul_f32 v[218:219], v[218:219], v[228:229]
	v_pk_mul_f32 v[220:221], v[220:221], v[230:231]
	v_pk_mul_f32 v[222:223], v[222:223], v[232:233]
	v_pk_mul_f32 v[224:225], v[224:225], v[234:235]
	v_pk_mul_f32 v[152:153], v[12:13], v[218:219]
	v_pk_mul_f32 v[154:155], v[14:15], v[220:221]
	v_pk_mul_f32 v[156:157], v[8:9], v[222:223]
	v_pk_mul_f32 v[158:159], v[10:11], v[224:225]
	v_cvt_f32_ubyte0_e32 v218, v196
	v_cvt_f32_ubyte1_e32 v219, v196
	v_cvt_f32_ubyte2_e32 v220, v196
	v_cvt_f32_ubyte3_e32 v221, v196
	v_cvt_f32_ubyte0_e32 v222, v197
	v_cvt_f32_ubyte1_e32 v223, v197
	v_cvt_f32_ubyte2_e32 v224, v197
	v_cvt_f32_ubyte3_e32 v225, v197
	v_max_f32_e32 v218, 1.0, v218
	v_max_f32_e32 v219, 1.0, v219
	v_max_f32_e32 v220, 1.0, v220
	v_max_f32_e32 v221, 1.0, v221
	v_max_f32_e32 v222, 1.0, v222
	v_max_f32_e32 v223, 1.0, v223
	v_max_f32_e32 v224, 1.0, v224
	v_max_f32_e32 v225, 1.0, v225
	v_rcp_f32_e32 v218, v218
	v_rcp_f32_e32 v219, v219
	v_rcp_f32_e32 v220, v220
	v_rcp_f32_e32 v221, v221
	v_rcp_f32_e32 v222, v222
	v_rcp_f32_e32 v223, v223
	v_rcp_f32_e32 v224, v224
	v_rcp_f32_e32 v225, v225
	v_cvt_f32_ubyte0_e32 v228, v212
	v_cvt_f32_ubyte1_e32 v229, v212
	v_cvt_f32_ubyte2_e32 v230, v212
	v_cvt_f32_ubyte3_e32 v231, v212
	v_cvt_f32_ubyte0_e32 v232, v213
	v_cvt_f32_ubyte1_e32 v233, v213
	v_cvt_f32_ubyte2_e32 v234, v213
	v_cvt_f32_ubyte3_e32 v235, v213
	v_pk_mul_f32 v[218:219], v[218:219], v[228:229]
	v_pk_mul_f32 v[220:221], v[220:221], v[230:231]
	v_pk_mul_f32 v[222:223], v[222:223], v[232:233]
	v_pk_mul_f32 v[224:225], v[224:225], v[234:235]
	v_pk_mul_f32 v[12:13], v[4:5], v[218:219]
	v_pk_mul_f32 v[14:15], v[6:7], v[220:221]
	v_pk_mul_f32 v[8:9], v[0:1], v[222:223]
	v_pk_mul_f32 v[10:11], v[2:3], v[224:225]
	s_branch .Lp6_epi_done
; __device__ __forceinline__ unsigned cvt_pk_bf16(float lo, float hi) { f32x2_cv v = {lo, hi}; bf16x2_cv b = __builtin_convertvector(v, bf16x2_cv); return __builtin_bit_cast(unsigned, b); }
;     __device__ __forceinline__ void operator()(f32x4 (&acc)[2][2][4][2], const Unit& u, int wr, int wc, int fr, int fq) const {
;     ...
;                     const u32x2 gb = *(const u32x2*)(SG + row * SG_PITCH + 1024 + col0 + bj * HALF);
;                     float fb[8] = { (float)(gb.x & 255u), (float)((gb.x >> 8) & 255u), (float)((gb.x >> 16) & 255u), (float)(gb.x >> 24), (float)(gb.y & 255u), (float)((gb.y >> 8) & 255u), (float)((gb.y >> 16) & 255u), (float)(gb.y >> 24) };
; #pragma unroll
;                     for (int j = 0; j < 8; ++j) fb[j] = fmaxf(fb[j], 1.0f);
;                     if (!second) {
;                         const u32x2 ga = *(const u32x2*)(SG + row * SG_PITCH + col0 + bj * HALF);
;                         const float fa[8] = { (float)(ga.x & 255u), (float)((ga.x >> 8) & 255u), (float)((ga.x >> 16) & 255u), (float)(ga.x >> 24), (float)(ga.y & 255u), (float)((ga.y >> 8) & 255u), (float)((ga.y >> 16) & 255u), (float)(ga.y >> 24) };
; #pragma unroll
;                         for (int j = 0; j < 4; ++j) { acc[ai][bj][m][0][j] *= fa[j] * __builtin_amdgcn_rcpf(fb[j]); acc[ai][bj][m][1][j] *= fa[4 + j] * __builtin_amdgcn_rcpf(fb[4 + j]); }
;                     } else {
;                         const float q = 1.0f / 255.0f; const f32x4 a0 = acc[ai][bj][m][0], a1 = acc[ai][bj][m][1];
;                         u32x4 w; w.x = cvt_pk_bf16(fb[0] * q * a0[0], fb[1] * q * a0[1]); w.y = cvt_pk_bf16(fb[2] * q * a0[2], fb[3] * q * a0[3]);
;                         w.z = cvt_pk_bf16(fb[4] * q * a1[0], fb[5] * q * a1[1]); w.w = cvt_pk_bf16(fb[6] * q * a1[2], fb[7] * q * a1[3]);
;                         *(u32x4*)(T + row * 1024 + col0 + bj * HALF) = w;
;                     }
.Lp6_second:
	v_mov_b32_e32 v216, v176
	v_mov_b64_e32 v[214:215], s[36:37]
	v_mad_i64_i32 v[214:215], s[98:99], v216, s56, v[214:215]
	v_lshl_add_u64 v[214:215], v[214:215], 0, v[174:175]
	global_load_dwordx2 v[182:183], v[214:215], off offset:1024
	global_load_dwordx2 v[184:185], v[214:215], off offset:1152
	v_add_u32_e32 v216, 16, v176
	v_mov_b64_e32 v[214:215], s[36:37]
	v_mad_i64_i32 v[214:215], s[98:99], v216, s56, v[214:215]
	v_lshl_add_u64 v[214:215], v[214:215], 0, v[174:175]
	global_load_dwordx2 v[186:187], v[214:215], off offset:1024
	global_load_dwordx2 v[188:189], v[214:215], off offset:1152
	v_add_u32_e32 v216, 32, v176
	v_mov_b64_e32 v[214:215], s[36:37]
	v_mad_i64_i32 v[214:215], s[98:99], v216, s56, v[214:215]
	v_lshl_add_u64 v[214:215], v[214:215], 0, v[174:175]
	global_load_dwordx2 v[190:191], v[214:215], off offset:1024
	global_load_dwordx2 v[192:193], v[214:215], off offset:1152
	v_add_u32_e32 v216, 48, v176
	v_mov_b64_e32 v[214:215], s[36:37]
	v_mad_i64_i32 v[214:215], s[98:99], v216, s56, v[214:215]
	v_lshl_add_u64 v[214:215], v[214:215], 0, v[174:175]
	global_load_dwordx2 v[194:195], v[214:215], off offset:1024
	global_load_dwordx2 v[196:197], v[214:215], off offset:1152
	s_waitcnt vmcnt(6)
	v_mov_b32_e32 v216, v176
	v_lshlrev_b32_e32 v216, 11, v216
	v_lshl_add_u32 v214, v174, 1, v216
	v_mov_b32_e32 v215, 0
	v_lshl_add_u64 v[214:215], v[214:215], 0, s[30:31]
	v_cvt_f32_ubyte0_e32 v218, v182
	v_cvt_f32_ubyte1_e32 v219, v182
	v_cvt_f32_ubyte2_e32 v220, v182
	v_cvt_f32_ubyte3_e32 v221, v182
	v_cvt_f32_ubyte0_e32 v222, v183
	v_cvt_f32_ubyte1_e32 v223, v183
	v_cvt_f32_ubyte2_e32 v224, v183
	v_cvt_f32_ubyte3_e32 v225, v183
	v_max_f32_e32 v218, 1.0, v218
	v_max_f32_e32 v219, 1.0, v219
	v_max_f32_e32 v220, 1.0, v220
	v_max_f32_e32 v221, 1.0, v221
	v_max_f32_e32 v222, 1.0, v222
	v_max_f32_e32 v223, 1.0, v223
	v_max_f32_e32 v224, 1.0, v224
	v_max_f32_e32 v225, 1.0, v225
	v_pk_mul_f32 v[218:219], v[218:219], s[18:19] op_sel_hi:[1,0]
	v_pk_mul_f32 v[220:221], v[220:221], s[18:19] op_sel_hi:[1,0]
	v_pk_mul_f32 v[222:223], v[222:223], s[18:19] op_sel_hi:[1,0]
	v_pk_mul_f32 v[224:225], v[224:225], s[18:19] op_sel_hi:[1,0]
	v_pk_mul_f32 v[218:219], v[36:37], v[218:219]
	v_pk_mul_f32 v[220:221], v[38:39], v[220:221]
	v_pk_mul_f32 v[222:223], v[32:33], v[222:223]
	v_pk_mul_f32 v[224:225], v[34:35], v[224:225]
	v_cvt_pk_bf16_f32 v236, v218, v219
	v_cvt_pk_bf16_f32 v237, v220, v221
	v_cvt_pk_bf16_f32 v238, v222, v223
	v_cvt_pk_bf16_f32 v239, v224, v225
	global_store_dwordx4 v[214:215], v[236:239], off
	v_mov_b64_e32 v[16:17], v[36:37]
	v_mov_b64_e32 v[18:19], v[38:39]
	v_mov_b64_e32 v[20:21], v[32:33]
	v_mov_b64_e32 v[22:23], v[34:35]
	v_cvt_f32_ubyte0_e32 v218, v184
	v_cvt_f32_ubyte1_e32 v219, v184
	v_cvt_f32_ubyte2_e32 v220, v184
	v_cvt_f32_ubyte3_e32 v221, v184
	v_cvt_f32_ubyte0_e32 v222, v185
	v_cvt_f32_ubyte1_e32 v223, v185
	v_cvt_f32_ubyte2_e32 v224, v185
	v_cvt_f32_ubyte3_e32 v225, v185
	v_max_f32_e32 v218, 1.0, v218
	v_max_f32_e32 v219, 1.0, v219
	v_max_f32_e32 v220, 1.0, v220
	v_max_f32_e32 v221, 1.0, v221
	v_max_f32_e32 v222, 1.0, v222
	v_max_f32_e32 v223, 1.0, v223
	v_max_f32_e32 v224, 1.0, v224
	v_max_f32_e32 v225, 1.0, v225
	v_pk_mul_f32 v[218:219], v[218:219], s[18:19] op_sel_hi:[1,0]
	v_pk_mul_f32 v[220:221], v[220:221], s[18:19] op_sel_hi:[1,0]
	v_pk_mul_f32 v[222:223], v[222:223], s[18:19] op_sel_hi:[1,0]
	v_pk_mul_f32 v[224:225], v[224:225], s[18:19] op_sel_hi:[1,0]
	v_pk_mul_f32 v[218:219], v[156:157], v[218:219]
	v_pk_mul_f32 v[220:221], v[158:159], v[220:221]
	v_pk_mul_f32 v[222:223], v[152:153], v[222:223]
	v_pk_mul_f32 v[224:225], v[154:155], v[224:225]
	v_cvt_pk_bf16_f32 v240, v218, v219
	v_cvt_pk_bf16_f32 v241, v220, v221
	v_cvt_pk_bf16_f32 v242, v222, v223
	v_cvt_pk_bf16_f32 v243, v224, v225
	global_store_dwordx4 v[214:215], v[240:243], off offset:256
	v_mov_b64_e32 v[32:33], v[156:157]
	v_mov_b64_e32 v[34:35], v[158:159]
	v_mov_b64_e32 v[36:37], v[152:153]
	v_mov_b64_e32 v[38:39], v[154:155]
	s_waitcnt vmcnt(6)
	v_add_u32_e32 v216, 16, v176
	v_lshlrev_b32_e32 v216, 11, v216
	v_lshl_add_u32 v214, v174, 1, v216
	v_mov_b32_e32 v215, 0
	v_lshl_add_u64 v[214:215], v[214:215], 0, s[30:31]
	v_cvt_f32_ubyte0_e32 v218, v186
	v_cvt_f32_ubyte1_e32 v219, v186
	v_cvt_f32_ubyte2_e32 v220, v186
	v_cvt_f32_ubyte3_e32 v221, v186
	v_cvt_f32_ubyte0_e32 v222, v187
	v_cvt_f32_ubyte1_e32 v223, v187
	v_cvt_f32_ubyte2_e32 v224, v187
	v_cvt_f32_ubyte3_e32 v225, v187
	v_max_f32_e32 v218, 1.0, v218
	v_max_f32_e32 v219, 1.0, v219
	v_max_f32_e32 v220, 1.0, v220
	v_max_f32_e32 v221, 1.0, v221
	v_max_f32_e32 v222, 1.0, v222
	v_max_f32_e32 v223, 1.0, v223
	v_max_f32_e32 v224, 1.0, v224
	v_max_f32_e32 v225, 1.0, v225
	v_pk_mul_f32 v[218:219], v[218:219], s[18:19] op_sel_hi:[1,0]
	v_pk_mul_f32 v[220:221], v[220:221], s[18:19] op_sel_hi:[1,0]
	v_pk_mul_f32 v[222:223], v[222:223], s[18:19] op_sel_hi:[1,0]
	v_pk_mul_f32 v[224:225], v[224:225], s[18:19] op_sel_hi:[1,0]
	v_pk_mul_f32 v[218:219], v[68:69], v[218:219]
	v_pk_mul_f32 v[220:221], v[70:71], v[220:221]
	v_pk_mul_f32 v[222:223], v[64:65], v[222:223]
	v_pk_mul_f32 v[224:225], v[66:67], v[224:225]
	v_cvt_pk_bf16_f32 v236, v218, v219
	v_cvt_pk_bf16_f32 v237, v220, v221
	v_cvt_pk_bf16_f32 v238, v222, v223
	v_cvt_pk_bf16_f32 v239, v224, v225
	global_store_dwordx4 v[214:215], v[236:239], off
	v_mov_b64_e32 v[48:49], v[68:69]
	v_mov_b64_e32 v[50:51], v[70:71]
	v_mov_b64_e32 v[52:53], v[64:65]
	v_mov_b64_e32 v[54:55], v[66:67]
	v_cvt_f32_ubyte0_e32 v218, v188
	v_cvt_f32_ubyte1_e32 v219, v188
	v_cvt_f32_ubyte2_e32 v220, v188
	v_cvt_f32_ubyte3_e32 v221, v188
	v_cvt_f32_ubyte0_e32 v222, v189
	v_cvt_f32_ubyte1_e32 v223, v189
	v_cvt_f32_ubyte2_e32 v224, v189
	v_cvt_f32_ubyte3_e32 v225, v189
	v_max_f32_e32 v218, 1.0, v218
	v_max_f32_e32 v219, 1.0, v219
	v_max_f32_e32 v220, 1.0, v220
	v_max_f32_e32 v221, 1.0, v221
	v_max_f32_e32 v222, 1.0, v222
	v_max_f32_e32 v223, 1.0, v223
	v_max_f32_e32 v224, 1.0, v224
	v_max_f32_e32 v225, 1.0, v225
	v_pk_mul_f32 v[218:219], v[218:219], s[18:19] op_sel_hi:[1,0]
	v_pk_mul_f32 v[220:221], v[220:221], s[18:19] op_sel_hi:[1,0]
	v_pk_mul_f32 v[222:223], v[222:223], s[18:19] op_sel_hi:[1,0]
	v_pk_mul_f32 v[224:225], v[224:225], s[18:19] op_sel_hi:[1,0]
	v_pk_mul_f32 v[218:219], v[148:149], v[218:219]
	v_pk_mul_f32 v[220:221], v[150:151], v[220:221]
	v_pk_mul_f32 v[222:223], v[144:145], v[222:223]
	v_pk_mul_f32 v[224:225], v[146:147], v[224:225]
	v_cvt_pk_bf16_f32 v240, v218, v219
	v_cvt_pk_bf16_f32 v241, v220, v221
	v_cvt_pk_bf16_f32 v242, v222, v223
	v_cvt_pk_bf16_f32 v243, v224, v225
	global_store_dwordx4 v[214:215], v[240:243], off offset:256
	v_mov_b64_e32 v[64:65], v[148:149]
	v_mov_b64_e32 v[66:67], v[150:151]
	v_mov_b64_e32 v[68:69], v[144:145]
	v_mov_b64_e32 v[70:71], v[146:147]
	s_waitcnt vmcnt(6)
; __device__ __forceinline__ unsigned cvt_pk_bf16(float lo, float hi) { f32x2_cv v = {lo, hi}; bf16x2_cv b = __builtin_convertvector(v, bf16x2_cv); return __builtin_bit_cast(unsigned, b); }
;     __device__ __forceinline__ void operator()(f32x4 (&acc)[2][2][4][2], const Unit& u, int wr, int wc, int fr, int fq) const {
;     ...
;                     const u32x2 gb = *(const u32x2*)(SG + row * SG_PITCH + 1024 + col0 + bj * HALF);
;                     float fb[8] = { (float)(gb.x & 255u), (float)((gb.x >> 8) & 255u), (float)((gb.x >> 16) & 255u), (float)(gb.x >> 24), (float)(gb.y & 255u), (float)((gb.y >> 8) & 255u), (float)((gb.y >> 16) & 255u), (float)(gb.y >> 24) };
; #pragma unroll
;                     for (int j = 0; j < 8; ++j) fb[j] = fmaxf(fb[j], 1.0f);
;                     if (!second) {
;                         const u32x2 ga = *(const u32x2*)(SG + row * SG_PITCH + col0 + bj * HALF);
;                         const float fa[8] = { (float)(ga.x & 255u), (float)((ga.x >> 8) & 255u), (float)((ga.x >> 16) & 255u), (float)(ga.x >> 24), (float)(ga.y & 255u), (float)((ga.y >> 8) & 255u), (float)((ga.y >> 16) & 255u), (float)(ga.y >> 24) };
; #pragma unroll
;                         for (int j = 0; j < 4; ++j) { acc[ai][bj][m][0][j] *= fa[j] * __builtin_amdgcn_rcpf(fb[j]); acc[ai][bj][m][1][j] *= fa[4 + j] * __builtin_amdgcn_rcpf(fb[4 + j]); }
;                     } else {
;                         const float q = 1.0f / 255.0f; const f32x4 a0 = acc[ai][bj][m][0], a1 = acc[ai][bj][m][1];
;                         u32x4 w; w.x = cvt_pk_bf16(fb[0] * q * a0[0], fb[1] * q * a0[1]); w.y = cvt_pk_bf16(fb[2] * q * a0[2], fb[3] * q * a0[3]);
;                         w.z = cvt_pk_bf16(fb[4] * q * a1[0], fb[5] * q * a1[1]); w.w = cvt_pk_bf16(fb[6] * q * a1[2], fb[7] * q * a1[3]);
;                         *(u32x4*)(T + row * 1024 + col0 + bj * HALF) = w;
;                     }
	v_add_u32_e32 v216, 32, v176
	v_lshlrev_b32_e32 v216, 11, v216
	v_lshl_add_u32 v214, v174, 1, v216
	v_mov_b32_e32 v215, 0
	v_lshl_add_u64 v[214:215], v[214:215], 0, s[30:31]
	v_cvt_f32_ubyte0_e32 v218, v190
	v_cvt_f32_ubyte1_e32 v219, v190
	v_cvt_f32_ubyte2_e32 v220, v190
	v_cvt_f32_ubyte3_e32 v221, v190
	v_cvt_f32_ubyte0_e32 v222, v191
	v_cvt_f32_ubyte1_e32 v223, v191
	v_cvt_f32_ubyte2_e32 v224, v191
	v_cvt_f32_ubyte3_e32 v225, v191
	v_max_f32_e32 v218, 1.0, v218
	v_max_f32_e32 v219, 1.0, v219
	v_max_f32_e32 v220, 1.0, v220
	v_max_f32_e32 v221, 1.0, v221
	v_max_f32_e32 v222, 1.0, v222
	v_max_f32_e32 v223, 1.0, v223
	v_max_f32_e32 v224, 1.0, v224
	v_max_f32_e32 v225, 1.0, v225
	v_pk_mul_f32 v[218:219], v[218:219], s[18:19] op_sel_hi:[1,0]
	v_pk_mul_f32 v[220:221], v[220:221], s[18:19] op_sel_hi:[1,0]
	v_pk_mul_f32 v[222:223], v[222:223], s[18:19] op_sel_hi:[1,0]
	v_pk_mul_f32 v[224:225], v[224:225], s[18:19] op_sel_hi:[1,0]
	v_pk_mul_f32 v[218:219], v[100:101], v[218:219]
	v_pk_mul_f32 v[220:221], v[102:103], v[220:221]
	v_pk_mul_f32 v[222:223], v[96:97], v[222:223]
	v_pk_mul_f32 v[224:225], v[98:99], v[224:225]
	v_cvt_pk_bf16_f32 v236, v218, v219
	v_cvt_pk_bf16_f32 v237, v220, v221
	v_cvt_pk_bf16_f32 v238, v222, v223
	v_cvt_pk_bf16_f32 v239, v224, v225
	global_store_dwordx4 v[214:215], v[236:239], off
	v_mov_b64_e32 v[80:81], v[100:101]
	v_mov_b64_e32 v[82:83], v[102:103]
	v_mov_b64_e32 v[84:85], v[96:97]
	v_mov_b64_e32 v[86:87], v[98:99]
	v_cvt_f32_ubyte0_e32 v218, v192
	v_cvt_f32_ubyte1_e32 v219, v192
	v_cvt_f32_ubyte2_e32 v220, v192
	v_cvt_f32_ubyte3_e32 v221, v192
	v_cvt_f32_ubyte0_e32 v222, v193
	v_cvt_f32_ubyte1_e32 v223, v193
	v_cvt_f32_ubyte2_e32 v224, v193
	v_cvt_f32_ubyte3_e32 v225, v193
	v_max_f32_e32 v218, 1.0, v218
	v_max_f32_e32 v219, 1.0, v219
	v_max_f32_e32 v220, 1.0, v220
	v_max_f32_e32 v221, 1.0, v221
	v_max_f32_e32 v222, 1.0, v222
	v_max_f32_e32 v223, 1.0, v223
	v_max_f32_e32 v224, 1.0, v224
	v_max_f32_e32 v225, 1.0, v225
	v_pk_mul_f32 v[218:219], v[218:219], s[18:19] op_sel_hi:[1,0]
	v_pk_mul_f32 v[220:221], v[220:221], s[18:19] op_sel_hi:[1,0]
	v_pk_mul_f32 v[222:223], v[222:223], s[18:19] op_sel_hi:[1,0]
	v_pk_mul_f32 v[224:225], v[224:225], s[18:19] op_sel_hi:[1,0]
	v_pk_mul_f32 v[218:219], v[140:141], v[218:219]
	v_pk_mul_f32 v[220:221], v[142:143], v[220:221]
	v_pk_mul_f32 v[222:223], v[136:137], v[222:223]
	v_pk_mul_f32 v[224:225], v[138:139], v[224:225]
	v_cvt_pk_bf16_f32 v240, v218, v219
	v_cvt_pk_bf16_f32 v241, v220, v221
	v_cvt_pk_bf16_f32 v242, v222, v223
	v_cvt_pk_bf16_f32 v243, v224, v225
	global_store_dwordx4 v[214:215], v[240:243], off offset:256
	v_mov_b64_e32 v[96:97], v[140:141]
	v_mov_b64_e32 v[98:99], v[142:143]
	v_mov_b64_e32 v[100:101], v[136:137]
	v_mov_b64_e32 v[102:103], v[138:139]
	s_waitcnt vmcnt(6)
	v_add_u32_e32 v216, 48, v176
	v_lshlrev_b32_e32 v216, 11, v216
	v_lshl_add_u32 v214, v174, 1, v216
	v_mov_b32_e32 v215, 0
	v_lshl_add_u64 v[214:215], v[214:215], 0, s[30:31]
	v_cvt_f32_ubyte0_e32 v218, v194
	v_cvt_f32_ubyte1_e32 v219, v194
	v_cvt_f32_ubyte2_e32 v220, v194
	v_cvt_f32_ubyte3_e32 v221, v194
	v_cvt_f32_ubyte0_e32 v222, v195
	v_cvt_f32_ubyte1_e32 v223, v195
	v_cvt_f32_ubyte2_e32 v224, v195
	v_cvt_f32_ubyte3_e32 v225, v195
	v_max_f32_e32 v218, 1.0, v218
	v_max_f32_e32 v219, 1.0, v219
	v_max_f32_e32 v220, 1.0, v220
	v_max_f32_e32 v221, 1.0, v221
	v_max_f32_e32 v222, 1.0, v222
	v_max_f32_e32 v223, 1.0, v223
	v_max_f32_e32 v224, 1.0, v224
	v_max_f32_e32 v225, 1.0, v225
	v_pk_mul_f32 v[218:219], v[218:219], s[18:19] op_sel_hi:[1,0]
	v_pk_mul_f32 v[220:221], v[220:221], s[18:19] op_sel_hi:[1,0]
	v_pk_mul_f32 v[222:223], v[222:223], s[18:19] op_sel_hi:[1,0]
	v_pk_mul_f32 v[224:225], v[224:225], s[18:19] op_sel_hi:[1,0]
	v_pk_mul_f32 v[218:219], v[132:133], v[218:219]
	v_pk_mul_f32 v[220:221], v[134:135], v[220:221]
	v_pk_mul_f32 v[222:223], v[128:129], v[222:223]
	v_pk_mul_f32 v[224:225], v[130:131], v[224:225]
	v_cvt_pk_bf16_f32 v236, v218, v219
	v_cvt_pk_bf16_f32 v237, v220, v221
	v_cvt_pk_bf16_f32 v238, v222, v223
	v_cvt_pk_bf16_f32 v239, v224, v225
	global_store_dwordx4 v[214:215], v[236:239], off
	v_mov_b64_e32 v[112:113], v[132:133]
	v_mov_b64_e32 v[114:115], v[134:135]
	v_mov_b64_e32 v[116:117], v[128:129]
	v_mov_b64_e32 v[118:119], v[130:131]
	v_cvt_f32_ubyte0_e32 v218, v196
	v_cvt_f32_ubyte1_e32 v219, v196
	v_cvt_f32_ubyte2_e32 v220, v196
	v_cvt_f32_ubyte3_e32 v221, v196
	v_cvt_f32_ubyte0_e32 v222, v197
	v_cvt_f32_ubyte1_e32 v223, v197
	v_cvt_f32_ubyte2_e32 v224, v197
	v_cvt_f32_ubyte3_e32 v225, v197
	v_max_f32_e32 v218, 1.0, v218
	v_max_f32_e32 v219, 1.0, v219
	v_max_f32_e32 v220, 1.0, v220
	v_max_f32_e32 v221, 1.0, v221
	v_max_f32_e32 v222, 1.0, v222
	v_max_f32_e32 v223, 1.0, v223
	v_max_f32_e32 v224, 1.0, v224
	v_max_f32_e32 v225, 1.0, v225
	v_pk_mul_f32 v[218:219], v[218:219], s[18:19] op_sel_hi:[1,0]
	v_pk_mul_f32 v[220:221], v[220:221], s[18:19] op_sel_hi:[1,0]
	v_pk_mul_f32 v[222:223], v[222:223], s[18:19] op_sel_hi:[1,0]
	v_pk_mul_f32 v[224:225], v[224:225], s[18:19] op_sel_hi:[1,0]
	v_pk_mul_f32 v[218:219], v[124:125], v[218:219]
	v_pk_mul_f32 v[220:221], v[126:127], v[220:221]
	v_pk_mul_f32 v[222:223], v[120:121], v[222:223]
	v_pk_mul_f32 v[224:225], v[122:123], v[224:225]
	v_cvt_pk_bf16_f32 v240, v218, v219
	v_cvt_pk_bf16_f32 v241, v220, v221
	v_cvt_pk_bf16_f32 v242, v222, v223
	v_cvt_pk_bf16_f32 v243, v224, v225
	global_store_dwordx4 v[214:215], v[240:243], off offset:256
	v_mov_b64_e32 v[128:129], v[124:125]
	v_mov_b64_e32 v[130:131], v[126:127]
	v_mov_b64_e32 v[132:133], v[120:121]
	v_mov_b64_e32 v[134:135], v[122:123]
	v_add_u32_e32 v216, 128, v176
	v_mov_b64_e32 v[214:215], s[36:37]
	v_mad_i64_i32 v[214:215], s[98:99], v216, s56, v[214:215]
	v_lshl_add_u64 v[214:215], v[214:215], 0, v[174:175]
	global_load_dwordx2 v[182:183], v[214:215], off offset:1024
	global_load_dwordx2 v[184:185], v[214:215], off offset:1152
	v_add_u32_e32 v216, 144, v176
	v_mov_b64_e32 v[214:215], s[36:37]
	v_mad_i64_i32 v[214:215], s[98:99], v216, s56, v[214:215]
	v_lshl_add_u64 v[214:215], v[214:215], 0, v[174:175]
	global_load_dwordx2 v[186:187], v[214:215], off offset:1024
	global_load_dwordx2 v[188:189], v[214:215], off offset:1152
	v_add_u32_e32 v216, 160, v176
	v_mov_b64_e32 v[214:215], s[36:37]
	v_mad_i64_i32 v[214:215], s[98:99], v216, s56, v[214:215]
	v_lshl_add_u64 v[214:215], v[214:215], 0, v[174:175]
	global_load_dwordx2 v[190:191], v[214:215], off offset:1024
	global_load_dwordx2 v[192:193], v[214:215], off offset:1152
	v_add_u32_e32 v216, 176, v176
	v_mov_b64_e32 v[214:215], s[36:37]
	v_mad_i64_i32 v[214:215], s[98:99], v216, s56, v[214:215]
	v_lshl_add_u64 v[214:215], v[214:215], 0, v[174:175]
	global_load_dwordx2 v[194:195], v[214:215], off offset:1024
	global_load_dwordx2 v[196:197], v[214:215], off offset:1152
	s_waitcnt vmcnt(6)
; __device__ __forceinline__ unsigned cvt_pk_bf16(float lo, float hi) { f32x2_cv v = {lo, hi}; bf16x2_cv b = __builtin_convertvector(v, bf16x2_cv); return __builtin_bit_cast(unsigned, b); }
;     __device__ __forceinline__ void operator()(f32x4 (&acc)[2][2][4][2], const Unit& u, int wr, int wc, int fr, int fq) const {
;     ...
;                     const u32x2 gb = *(const u32x2*)(SG + row * SG_PITCH + 1024 + col0 + bj * HALF);
;                     float fb[8] = { (float)(gb.x & 255u), (float)((gb.x >> 8) & 255u), (float)((gb.x >> 16) & 255u), (float)(gb.x >> 24), (float)(gb.y & 255u), (float)((gb.y >> 8) & 255u), (float)((gb.y >> 16) & 255u), (float)(gb.y >> 24) };
; #pragma unroll
;                     for (int j = 0; j < 8; ++j) fb[j] = fmaxf(fb[j], 1.0f);
;                     if (!second) {
;                         const u32x2 ga = *(const u32x2*)(SG + row * SG_PITCH + col0 + bj * HALF);
;                         const float fa[8] = { (float)(ga.x & 255u), (float)((ga.x >> 8) & 255u), (float)((ga.x >> 16) & 255u), (float)(ga.x >> 24), (float)(ga.y & 255u), (float)((ga.y >> 8) & 255u), (float)((ga.y >> 16) & 255u), (float)(ga.y >> 24) };
; #pragma unroll
;                         for (int j = 0; j < 4; ++j) { acc[ai][bj][m][0][j] *= fa[j] * __builtin_amdgcn_rcpf(fb[j]); acc[ai][bj][m][1][j] *= fa[4 + j] * __builtin_amdgcn_rcpf(fb[4 + j]); }
;                     } else {
;                         const float q = 1.0f / 255.0f; const f32x4 a0 = acc[ai][bj][m][0], a1 = acc[ai][bj][m][1];
;                         u32x4 w; w.x = cvt_pk_bf16(fb[0] * q * a0[0], fb[1] * q * a0[1]); w.y = cvt_pk_bf16(fb[2] * q * a0[2], fb[3] * q * a0[3]);
;                         w.z = cvt_pk_bf16(fb[4] * q * a1[0], fb[5] * q * a1[1]); w.w = cvt_pk_bf16(fb[6] * q * a1[2], fb[7] * q * a1[3]);
;                         *(u32x4*)(T + row * 1024 + col0 + bj * HALF) = w;
;                     }
	v_add_u32_e32 v216, 128, v176
	v_lshlrev_b32_e32 v216, 11, v216
	v_lshl_add_u32 v214, v174, 1, v216
	v_mov_b32_e32 v215, 0
	v_lshl_add_u64 v[214:215], v[214:215], 0, s[30:31]
	v_cvt_f32_ubyte0_e32 v218, v182
	v_cvt_f32_ubyte1_e32 v219, v182
	v_cvt_f32_ubyte2_e32 v220, v182
	v_cvt_f32_ubyte3_e32 v221, v182
	v_cvt_f32_ubyte0_e32 v222, v183
	v_cvt_f32_ubyte1_e32 v223, v183
	v_cvt_f32_ubyte2_e32 v224, v183
	v_cvt_f32_ubyte3_e32 v225, v183
	v_max_f32_e32 v218, 1.0, v218
	v_max_f32_e32 v219, 1.0, v219
	v_max_f32_e32 v220, 1.0, v220
	v_max_f32_e32 v221, 1.0, v221
	v_max_f32_e32 v222, 1.0, v222
	v_max_f32_e32 v223, 1.0, v223
	v_max_f32_e32 v224, 1.0, v224
	v_max_f32_e32 v225, 1.0, v225
	v_pk_mul_f32 v[218:219], v[218:219], s[18:19] op_sel_hi:[1,0]
	v_pk_mul_f32 v[220:221], v[220:221], s[18:19] op_sel_hi:[1,0]
	v_pk_mul_f32 v[222:223], v[222:223], s[18:19] op_sel_hi:[1,0]
	v_pk_mul_f32 v[224:225], v[224:225], s[18:19] op_sel_hi:[1,0]
	v_pk_mul_f32 v[218:219], v[108:109], v[218:219]
	v_pk_mul_f32 v[220:221], v[110:111], v[220:221]
	v_pk_mul_f32 v[222:223], v[104:105], v[222:223]
	v_pk_mul_f32 v[224:225], v[106:107], v[224:225]
	v_cvt_pk_bf16_f32 v236, v218, v219
	v_cvt_pk_bf16_f32 v237, v220, v221
	v_cvt_pk_bf16_f32 v238, v222, v223
	v_cvt_pk_bf16_f32 v239, v224, v225
	global_store_dwordx4 v[214:215], v[236:239], off
	v_mov_b64_e32 v[120:121], v[108:109]
	v_mov_b64_e32 v[122:123], v[110:111]
	v_mov_b64_e32 v[124:125], v[104:105]
	v_mov_b64_e32 v[126:127], v[106:107]
	v_cvt_f32_ubyte0_e32 v218, v184
	v_cvt_f32_ubyte1_e32 v219, v184
	v_cvt_f32_ubyte2_e32 v220, v184
	v_cvt_f32_ubyte3_e32 v221, v184
	v_cvt_f32_ubyte0_e32 v222, v185
	v_cvt_f32_ubyte1_e32 v223, v185
	v_cvt_f32_ubyte2_e32 v224, v185
	v_cvt_f32_ubyte3_e32 v225, v185
	v_max_f32_e32 v218, 1.0, v218
	v_max_f32_e32 v219, 1.0, v219
	v_max_f32_e32 v220, 1.0, v220
	v_max_f32_e32 v221, 1.0, v221
	v_max_f32_e32 v222, 1.0, v222
	v_max_f32_e32 v223, 1.0, v223
	v_max_f32_e32 v224, 1.0, v224
	v_max_f32_e32 v225, 1.0, v225
	v_pk_mul_f32 v[218:219], v[218:219], s[18:19] op_sel_hi:[1,0]
	v_pk_mul_f32 v[220:221], v[220:221], s[18:19] op_sel_hi:[1,0]
	v_pk_mul_f32 v[222:223], v[222:223], s[18:19] op_sel_hi:[1,0]
	v_pk_mul_f32 v[224:225], v[224:225], s[18:19] op_sel_hi:[1,0]
	v_pk_mul_f32 v[218:219], v[92:93], v[218:219]
	v_pk_mul_f32 v[220:221], v[94:95], v[220:221]
	v_pk_mul_f32 v[222:223], v[88:89], v[222:223]
	v_pk_mul_f32 v[224:225], v[90:91], v[224:225]
	v_cvt_pk_bf16_f32 v240, v218, v219
	v_cvt_pk_bf16_f32 v241, v220, v221
	v_cvt_pk_bf16_f32 v242, v222, v223
	v_cvt_pk_bf16_f32 v243, v224, v225
	global_store_dwordx4 v[214:215], v[240:243], off offset:256
	v_mov_b64_e32 v[104:105], v[92:93]
	v_mov_b64_e32 v[106:107], v[94:95]
	v_mov_b64_e32 v[108:109], v[88:89]
	v_mov_b64_e32 v[110:111], v[90:91]
	s_waitcnt vmcnt(6)
	v_add_u32_e32 v216, 144, v176
	v_lshlrev_b32_e32 v216, 11, v216
	v_lshl_add_u32 v214, v174, 1, v216
	v_mov_b32_e32 v215, 0
	v_lshl_add_u64 v[214:215], v[214:215], 0, s[30:31]
	v_cvt_f32_ubyte0_e32 v218, v186
	v_cvt_f32_ubyte1_e32 v219, v186
	v_cvt_f32_ubyte2_e32 v220, v186
	v_cvt_f32_ubyte3_e32 v221, v186
	v_cvt_f32_ubyte0_e32 v222, v187
	v_cvt_f32_ubyte1_e32 v223, v187
	v_cvt_f32_ubyte2_e32 v224, v187
	v_cvt_f32_ubyte3_e32 v225, v187
	v_max_f32_e32 v218, 1.0, v218
	v_max_f32_e32 v219, 1.0, v219
	v_max_f32_e32 v220, 1.0, v220
	v_max_f32_e32 v221, 1.0, v221
	v_max_f32_e32 v222, 1.0, v222
	v_max_f32_e32 v223, 1.0, v223
	v_max_f32_e32 v224, 1.0, v224
	v_max_f32_e32 v225, 1.0, v225
	v_pk_mul_f32 v[218:219], v[218:219], s[18:19] op_sel_hi:[1,0]
	v_pk_mul_f32 v[220:221], v[220:221], s[18:19] op_sel_hi:[1,0]
	v_pk_mul_f32 v[222:223], v[222:223], s[18:19] op_sel_hi:[1,0]
	v_pk_mul_f32 v[224:225], v[224:225], s[18:19] op_sel_hi:[1,0]
	v_pk_mul_f32 v[218:219], v[76:77], v[218:219]
	v_pk_mul_f32 v[220:221], v[78:79], v[220:221]
	v_pk_mul_f32 v[222:223], v[72:73], v[222:223]
	v_pk_mul_f32 v[224:225], v[74:75], v[224:225]
	v_cvt_pk_bf16_f32 v236, v218, v219
	v_cvt_pk_bf16_f32 v237, v220, v221
	v_cvt_pk_bf16_f32 v238, v222, v223
	v_cvt_pk_bf16_f32 v239, v224, v225
	global_store_dwordx4 v[214:215], v[236:239], off
	v_mov_b64_e32 v[136:137], v[76:77]
	v_mov_b64_e32 v[138:139], v[78:79]
	v_mov_b64_e32 v[140:141], v[72:73]
	v_mov_b64_e32 v[142:143], v[74:75]
	v_cvt_f32_ubyte0_e32 v218, v188
	v_cvt_f32_ubyte1_e32 v219, v188
	v_cvt_f32_ubyte2_e32 v220, v188
	v_cvt_f32_ubyte3_e32 v221, v188
	v_cvt_f32_ubyte0_e32 v222, v189
	v_cvt_f32_ubyte1_e32 v223, v189
	v_cvt_f32_ubyte2_e32 v224, v189
	v_cvt_f32_ubyte3_e32 v225, v189
	v_max_f32_e32 v218, 1.0, v218
	v_max_f32_e32 v219, 1.0, v219
	v_max_f32_e32 v220, 1.0, v220
	v_max_f32_e32 v221, 1.0, v221
	v_max_f32_e32 v222, 1.0, v222
	v_max_f32_e32 v223, 1.0, v223
	v_max_f32_e32 v224, 1.0, v224
	v_max_f32_e32 v225, 1.0, v225
	v_pk_mul_f32 v[218:219], v[218:219], s[18:19] op_sel_hi:[1,0]
	v_pk_mul_f32 v[220:221], v[220:221], s[18:19] op_sel_hi:[1,0]
	v_pk_mul_f32 v[222:223], v[222:223], s[18:19] op_sel_hi:[1,0]
	v_pk_mul_f32 v[224:225], v[224:225], s[18:19] op_sel_hi:[1,0]
	v_pk_mul_f32 v[218:219], v[60:61], v[218:219]
	v_pk_mul_f32 v[220:221], v[62:63], v[220:221]
	v_pk_mul_f32 v[222:223], v[56:57], v[222:223]
	v_pk_mul_f32 v[224:225], v[58:59], v[224:225]
	v_cvt_pk_bf16_f32 v240, v218, v219
	v_cvt_pk_bf16_f32 v241, v220, v221
	v_cvt_pk_bf16_f32 v242, v222, v223
	v_cvt_pk_bf16_f32 v243, v224, v225
	global_store_dwordx4 v[214:215], v[240:243], off offset:256
	v_mov_b64_e32 v[72:73], v[60:61]
	v_mov_b64_e32 v[74:75], v[62:63]
	v_mov_b64_e32 v[76:77], v[56:57]
	v_mov_b64_e32 v[78:79], v[58:59]
	s_waitcnt vmcnt(6)
; template <class Epi, class Sched, bool ALIGN_EPI = false, bool SP2 = false>
; __device__ __forceinline__ void gemm_phase(PG8_LAS unsigned char* lds, const Gemm g, const Sched& S, const Epi& E) {
;     ...
;         if (!has_next) break;
;         if constexpr (!Epi::CHAIN) {
; #pragma unroll
;         for (int a = 0; a < 2; ++a)
; #pragma unroll
;             for (int b = 0; b < 2; ++b)
; #pragma unroll
;                 for (int m = 0; m < 4; ++m)
; #pragma unroll
;                     for (int n = 0; n < 2; ++n) acc[a][b][m][n] = (f32x4){0.f, 0.f, 0.f, 0.f};
;         }
;         cur = nxt; cA = nA; cB = nB; ++ui;
;         if constexpr (ALIGN_EPI) { if (wr == 1) PG8_BAR; }
;     __device__ __forceinline__ void operator()(f32x4 (&acc)[2][2][4][2], const Unit& u, int wr, int wc, int fr, int fq) const {
;     ...
;                     const u32x2 gb = *(const u32x2*)(SG + row * SG_PITCH + 1024 + col0 + bj * HALF);
;                     float fb[8] = { (float)(gb.x & 255u), (float)((gb.x >> 8) & 255u), (float)((gb.x >> 16) & 255u), (float)(gb.x >> 24), (float)(gb.y & 255u), (float)((gb.y >> 8) & 255u), (float)((gb.y >> 16) & 255u), (float)(gb.y >> 24) };
; #pragma unroll
;                     for (int j = 0; j < 8; ++j) fb[j] = fmaxf(fb[j], 1.0f);
;                     if (!second) {
;                         const u32x2 ga = *(const u32x2*)(SG + row * SG_PITCH + col0 + bj * HALF);
;                         const float fa[8] = { (float)(ga.x & 255u), (float)((ga.x >> 8) & 255u), (float)((ga.x >> 16) & 255u), (float)(ga.x >> 24), (float)(ga.y & 255u), (float)((ga.y >> 8) & 255u), (float)((ga.y >> 16) & 255u), (float)(ga.y >> 24) };
; #pragma unroll
;                         for (int j = 0; j < 4; ++j) { acc[ai][bj][m][0][j] *= fa[j] * __builtin_amdgcn_rcpf(fb[j]); acc[ai][bj][m][1][j] *= fa[4 + j] * __builtin_amdgcn_rcpf(fb[4 + j]); }
;                     } else {
;                         const float q = 1.0f / 255.0f; const f32x4 a0 = acc[ai][bj][m][0], a1 = acc[ai][bj][m][1];
;                         u32x4 w; w.x = cvt_pk_bf16(fb[0] * q * a0[0], fb[1] * q * a0[1]); w.y = cvt_pk_bf16(fb[2] * q * a0[2], fb[3] * q * a0[3]);
;                         w.z = cvt_pk_bf16(fb[4] * q * a1[0], fb[5] * q * a1[1]); w.w = cvt_pk_bf16(fb[6] * q * a1[2], fb[7] * q * a1[3]);
;                         *(u32x4*)(T + row * 1024 + col0 + bj * HALF) = w;
;                     }
	v_add_u32_e32 v216, 160, v176
	v_lshlrev_b32_e32 v216, 11, v216
	v_lshl_add_u32 v214, v174, 1, v216
	v_mov_b32_e32 v215, 0
	v_lshl_add_u64 v[214:215], v[214:215], 0, s[30:31]
	v_cvt_f32_ubyte0_e32 v218, v190
	v_cvt_f32_ubyte1_e32 v219, v190
	v_cvt_f32_ubyte2_e32 v220, v190
	v_cvt_f32_ubyte3_e32 v221, v190
	v_cvt_f32_ubyte0_e32 v222, v191
	v_cvt_f32_ubyte1_e32 v223, v191
	v_cvt_f32_ubyte2_e32 v224, v191
	v_cvt_f32_ubyte3_e32 v225, v191
	v_max_f32_e32 v218, 1.0, v218
	v_max_f32_e32 v219, 1.0, v219
	v_max_f32_e32 v220, 1.0, v220
	v_max_f32_e32 v221, 1.0, v221
	v_max_f32_e32 v222, 1.0, v222
	v_max_f32_e32 v223, 1.0, v223
	v_max_f32_e32 v224, 1.0, v224
	v_max_f32_e32 v225, 1.0, v225
	v_pk_mul_f32 v[218:219], v[218:219], s[18:19] op_sel_hi:[1,0]
	v_pk_mul_f32 v[220:221], v[220:221], s[18:19] op_sel_hi:[1,0]
	v_pk_mul_f32 v[222:223], v[222:223], s[18:19] op_sel_hi:[1,0]
	v_pk_mul_f32 v[224:225], v[224:225], s[18:19] op_sel_hi:[1,0]
	v_pk_mul_f32 v[218:219], v[44:45], v[218:219]
	v_pk_mul_f32 v[220:221], v[46:47], v[220:221]
	v_pk_mul_f32 v[222:223], v[40:41], v[222:223]
	v_pk_mul_f32 v[224:225], v[42:43], v[224:225]
	v_cvt_pk_bf16_f32 v236, v218, v219
	v_cvt_pk_bf16_f32 v237, v220, v221
	v_cvt_pk_bf16_f32 v238, v222, v223
	v_cvt_pk_bf16_f32 v239, v224, v225
	global_store_dwordx4 v[214:215], v[236:239], off
	v_mov_b64_e32 v[144:145], v[44:45]
	v_mov_b64_e32 v[146:147], v[46:47]
	v_mov_b64_e32 v[148:149], v[40:41]
	v_mov_b64_e32 v[150:151], v[42:43]
	v_cvt_f32_ubyte0_e32 v218, v192
	v_cvt_f32_ubyte1_e32 v219, v192
	v_cvt_f32_ubyte2_e32 v220, v192
	v_cvt_f32_ubyte3_e32 v221, v192
	v_cvt_f32_ubyte0_e32 v222, v193
	v_cvt_f32_ubyte1_e32 v223, v193
	v_cvt_f32_ubyte2_e32 v224, v193
	v_cvt_f32_ubyte3_e32 v225, v193
	v_max_f32_e32 v218, 1.0, v218
	v_max_f32_e32 v219, 1.0, v219
	v_max_f32_e32 v220, 1.0, v220
	v_max_f32_e32 v221, 1.0, v221
	v_max_f32_e32 v222, 1.0, v222
	v_max_f32_e32 v223, 1.0, v223
	v_max_f32_e32 v224, 1.0, v224
	v_max_f32_e32 v225, 1.0, v225
	v_pk_mul_f32 v[218:219], v[218:219], s[18:19] op_sel_hi:[1,0]
	v_pk_mul_f32 v[220:221], v[220:221], s[18:19] op_sel_hi:[1,0]
	v_pk_mul_f32 v[222:223], v[222:223], s[18:19] op_sel_hi:[1,0]
	v_pk_mul_f32 v[224:225], v[224:225], s[18:19] op_sel_hi:[1,0]
	v_pk_mul_f32 v[218:219], v[28:29], v[218:219]
	v_pk_mul_f32 v[220:221], v[30:31], v[220:221]
	v_pk_mul_f32 v[222:223], v[24:25], v[222:223]
	v_pk_mul_f32 v[224:225], v[26:27], v[224:225]
	v_cvt_pk_bf16_f32 v240, v218, v219
	v_cvt_pk_bf16_f32 v241, v220, v221
	v_cvt_pk_bf16_f32 v242, v222, v223
	v_cvt_pk_bf16_f32 v243, v224, v225
	global_store_dwordx4 v[214:215], v[240:243], off offset:256
	v_mov_b64_e32 v[40:41], v[28:29]
	v_mov_b64_e32 v[42:43], v[30:31]
	v_mov_b64_e32 v[44:45], v[24:25]
	v_mov_b64_e32 v[46:47], v[26:27]
	s_waitcnt vmcnt(6)
	v_add_u32_e32 v216, 176, v176
	v_lshlrev_b32_e32 v216, 11, v216
	v_lshl_add_u32 v214, v174, 1, v216
	v_mov_b32_e32 v215, 0
	v_lshl_add_u64 v[214:215], v[214:215], 0, s[30:31]
	v_cvt_f32_ubyte0_e32 v218, v194
	v_cvt_f32_ubyte1_e32 v219, v194
	v_cvt_f32_ubyte2_e32 v220, v194
	v_cvt_f32_ubyte3_e32 v221, v194
	v_cvt_f32_ubyte0_e32 v222, v195
	v_cvt_f32_ubyte1_e32 v223, v195
	v_cvt_f32_ubyte2_e32 v224, v195
	v_cvt_f32_ubyte3_e32 v225, v195
	v_max_f32_e32 v218, 1.0, v218
	v_max_f32_e32 v219, 1.0, v219
	v_max_f32_e32 v220, 1.0, v220
	v_max_f32_e32 v221, 1.0, v221
	v_max_f32_e32 v222, 1.0, v222
	v_max_f32_e32 v223, 1.0, v223
	v_max_f32_e32 v224, 1.0, v224
	v_max_f32_e32 v225, 1.0, v225
	v_pk_mul_f32 v[218:219], v[218:219], s[18:19] op_sel_hi:[1,0]
	v_pk_mul_f32 v[220:221], v[220:221], s[18:19] op_sel_hi:[1,0]
	v_pk_mul_f32 v[222:223], v[222:223], s[18:19] op_sel_hi:[1,0]
	v_pk_mul_f32 v[224:225], v[224:225], s[18:19] op_sel_hi:[1,0]
	v_pk_mul_f32 v[218:219], v[12:13], v[218:219]
	v_pk_mul_f32 v[220:221], v[14:15], v[220:221]
	v_pk_mul_f32 v[222:223], v[8:9], v[222:223]
	v_pk_mul_f32 v[224:225], v[10:11], v[224:225]
	v_cvt_pk_bf16_f32 v236, v218, v219
	v_cvt_pk_bf16_f32 v237, v220, v221
	v_cvt_pk_bf16_f32 v238, v222, v223
	v_cvt_pk_bf16_f32 v239, v224, v225
	global_store_dwordx4 v[214:215], v[236:239], off
	v_mov_b64_e32 v[152:153], v[12:13]
	v_mov_b64_e32 v[154:155], v[14:15]
	v_mov_b64_e32 v[156:157], v[8:9]
	v_mov_b64_e32 v[158:159], v[10:11]
	v_cvt_f32_ubyte0_e32 v218, v196
	v_cvt_f32_ubyte1_e32 v219, v196
	v_cvt_f32_ubyte2_e32 v220, v196
	v_cvt_f32_ubyte3_e32 v221, v196
	v_cvt_f32_ubyte0_e32 v222, v197
	v_cvt_f32_ubyte1_e32 v223, v197
	v_cvt_f32_ubyte2_e32 v224, v197
	v_cvt_f32_ubyte3_e32 v225, v197
	v_max_f32_e32 v218, 1.0, v218
	v_max_f32_e32 v219, 1.0, v219
	v_max_f32_e32 v220, 1.0, v220
	v_max_f32_e32 v221, 1.0, v221
	v_max_f32_e32 v222, 1.0, v222
	v_max_f32_e32 v223, 1.0, v223
	v_max_f32_e32 v224, 1.0, v224
	v_max_f32_e32 v225, 1.0, v225
	v_pk_mul_f32 v[218:219], v[218:219], s[18:19] op_sel_hi:[1,0]
	v_pk_mul_f32 v[220:221], v[220:221], s[18:19] op_sel_hi:[1,0]
	v_pk_mul_f32 v[222:223], v[222:223], s[18:19] op_sel_hi:[1,0]
	v_pk_mul_f32 v[224:225], v[224:225], s[18:19] op_sel_hi:[1,0]
	v_pk_mul_f32 v[218:219], v[4:5], v[218:219]
	v_pk_mul_f32 v[220:221], v[6:7], v[220:221]
	v_pk_mul_f32 v[222:223], v[0:1], v[222:223]
	v_pk_mul_f32 v[224:225], v[2:3], v[224:225]
	v_cvt_pk_bf16_f32 v240, v218, v219
	v_cvt_pk_bf16_f32 v241, v220, v221
	v_cvt_pk_bf16_f32 v242, v222, v223
	v_cvt_pk_bf16_f32 v243, v224, v225
	global_store_dwordx4 v[214:215], v[240:243], off offset:256
	v_mov_b64_e32 v[12:13], v[4:5]
	v_mov_b64_e32 v[14:15], v[6:7]
	v_mov_b64_e32 v[8:9], v[0:1]
	v_mov_b64_e32 v[10:11], v[2:3]
.Lp6_epi_done:
	s_and_b64 vcc, exec, s[4:5]
	s_mov_b64 s[4:5], -1
	s_cbranch_vccnz .LBB0_645
.LBB0_715:
	s_andn2_b64 vcc, exec, s[8:9]
	s_cbranch_vccnz .LBB0_644
	s_barrier
	s_branch .LBB0_644
